# P3: wave 0 issues step-A loads before finishing step 0 (step-0 block moved after the loads, temporaries renamed), barrier after
# speedup vs baseline: 1.1032x; 1.0028x over previous
; #define LAS __attribute__((address_space(3)))
; __device__ __forceinline__ float exp_f(float x) { return __builtin_amdgcn_exp2f(x * 1.4426950408889634f); }
; __device__ __forceinline__ float sigmoid_f(float x) { return rcp_f(1.f + exp_f(-x)); }
; __device__ __forceinline__ float softplus_f(float x) { return fmaxf(x, 0.f) + __logf(1.f + exp_f(-fabsf(x))); }
; #define LBAR() do { asm volatile("s_waitcnt lgkmcnt(0)" ::: "memory"); __builtin_amdgcn_s_barrier(); asm volatile("" ::: "memory"); } while (0)
; __device__ __forceinline__ void prep_task(LAS unsigned char* lds, const PrepP& P, int task, int tid, int lane, int wave) {
;     ...
;     if (wave == 0) {
;         const float* bar = P.ba + (size_t)(row0 + lane) * 16;
;         float g = -exp_f(P.alog[h]) * softplus_f(bar[8 + h] + P.dtb[h]);
; #pragma unroll
;         for (int o = 1; o < 64; o <<= 1) { const float v = __shfl_up(g, o); if (lane >= o) g += v; }
;         gcl[lane] = g; gcl[64 + lane] = sigmoid_f(bar[h]);
;         if (lane == 63) P.gl[task] = exp_f(g);
;     }
;     LBAR();
;     {
;         const int t = tid >> 3, seg = tid & 7;
;         const float beta = gcl[64 + t], gc = gcl[t], glc = gcl[63];
;         const float eg = exp_f(gc), et = exp_f(glc - gc);
;         const int tt = n * 64 + t;
;         const bf16_t* zr = P.z + (size_t)(row0 + t) * NZ + 4096 + h * 128 + seg * 16;
;         const LAS float* cw = (const LAS float*)(lds + 114688) + seg * 16;
;         u32x4 xz[3][2][4];
; #pragma unroll
;         for (int m = 0; m < 3; ++m)
; #pragma unroll
;             for (int hf = 0; hf < 2; ++hf)
; #pragma unroll
;                 for (int j = 0; j < 4; ++j) { const bool ok = tt - 3 + j >= 0; xz[m][hf][j] = *(const u32x4*)(zr + m * 1024 + hf * 8 + (ptrdiff_t)(ok ? j - 3 : 0) * NZ); if (!ok) xz[m][hf][j] = (u32x4){0u, 0u, 0u, 0u}; }
.LBB0_416:
	v_mov_b32_e32 v55, v54
	v_mov_b32_e32 v48, 0
	s_and_b32 s8, s49, 0xffffffc0
	v_and_b32_e32 v0, -16, v48
	v_add_u32_e32 v58, 0, v0
	v_cndmask_b32_e64 v0, 0, 1, s[16:17]
	v_and_b32_e32 v56, 63, v55
	v_add_u32_e32 v63, 0x1b800, v58
	v_cmp_ne_u32_e64 s[4:5], 1, v0
	s_and_b64 s[98:99], exec, s[16:17]
	s_cbranch_scc0 .Lp3_a0_skip
	v_or_b32_e32 v200, s8, v56
	v_ashrrev_i32_e32 v201, 31, v200
	v_lshlrev_b64 v[200:201], 6, v[200:201]
	v_lshl_add_u64 v[200:201], v[44:45], 0, v[200:201]
	global_load_dword v202, v[46:47], off
	global_load_dword v203, v[200:201], off offset:32
	global_load_dword v204, v[42:43], off
	s_nop 0
	global_load_dword v200, v[200:201], off
.Lp3_a0_skip:
.LBB0_420:
	v_ashrrev_i32_e32 v26, 3, v55
	v_add_u32_e32 v0, s8, v26
	v_ashrrev_i32_e32 v1, 31, v0
	v_lshlrev_b64 v[0:1], 14, v[0:1]
	v_lshlrev_b32_e32 v2, 4, v55
	v_lshl_add_u64 v[0:1], v[40:41], 0, v[0:1]
	v_and_b32_e32 v60, 0x70, v2
	v_lshl_add_u64 v[0:1], v[0:1], 0, s[38:39]
	v_lshlrev_b32_e32 v152, 1, v60
	v_lshl_add_u64 v[4:5], v[0:1], 0, v[152:153]
	s_mov_b64 s[6:7], 0x13c02000
	s_and_b32 s9, s49, 0x7c0
	v_lshl_add_u64 v[6:7], v[4:5], 0, s[6:7]
	v_add_co_u32_e64 v12, s[6:7], s76, v4
	v_add_u32_e32 v27, s9, v26
	s_nop 0
	v_addc_co_u32_e64 v13, s[6:7], 0, v5, s[6:7]
	v_cmp_lt_i32_e32 vcc, 2, v27
	v_mov_b32_e32 v0, 0xffff4000
	v_cmp_lt_i32_e64 s[6:7], 0, v27
	v_cndmask_b32_e32 v8, 0, v0, vcc
	v_cmp_lt_i32_e64 s[8:9], 1, v27
	v_cndmask_b32_e64 v0, 0, -1, s[6:7]
	v_mov_b32_e32 v1, v0
	s_mov_b64 s[10:11], 0x13c03000
	v_cndmask_b32_e64 v9, 0, -1, vcc
	v_cndmask_b32_e64 v15, 0, -1, s[8:9]
	v_cndmask_b32_e64 v14, 0, v197, s[8:9]
	v_lshlrev_b64 v[24:25], 14, v[0:1]
	v_lshl_add_u64 v[32:33], v[4:5], 0, s[10:11]
	v_lshl_add_u64 v[10:11], v[6:7], 0, v[8:9]
	v_lshl_add_u64 v[28:29], v[6:7], 0, v[14:15]
	v_lshl_add_u64 v[30:31], v[6:7], 0, v[24:25]
	v_lshl_add_u64 v[4:5], v[32:33], 0, v[8:9]
	v_lshl_add_u64 v[8:9], v[32:33], 0, v[14:15]
	global_load_dwordx4 v[16:19], v[12:13], off offset:-4096
	global_load_dwordx4 v[20:23], v[10:11], off
	global_load_dwordx4 v[64:67], v[28:29], off
	global_load_dwordx4 v[68:71], v[30:31], off
	global_load_dwordx4 v[0:3], v[10:11], off offset:16
	global_load_dwordx4 v[72:75], v[10:11], off offset:2048
	global_load_dwordx4 v[76:79], v[28:29], off offset:2048
	global_load_dwordx4 v[80:83], v[30:31], off offset:2048
	global_load_dwordx4 v[94:97], v[6:7], off offset:2048
	global_load_dwordx4 v[98:101], v[10:11], off offset:2064
	global_load_dwordx4 v[102:105], v[28:29], off offset:2064
	global_load_dwordx4 v[106:109], v[30:31], off offset:2064
	global_load_dwordx4 v[110:113], v[6:7], off offset:2064
	global_load_dwordx4 v[114:117], v[4:5], off
	global_load_dwordx4 v[118:121], v[8:9], off
	v_lshl_add_u64 v[10:11], v[32:33], 0, v[24:25]
	global_load_dwordx4 v[122:125], v[10:11], off
	global_load_dwordx4 v[126:129], v[12:13], off
	s_and_b64 s[98:99], exec, s[16:17]
	s_cbranch_scc0 .Lp3_b0_skip
	s_mov_b64 s[98:99], vcc
	s_mov_b64 s[100:101], s[6:7]
	v_and_b32_e32 v201, 64, v192
	v_add_u32_e32 v205, -1, v192
	v_cmp_lt_i32_e32 vcc, v205, v201
	v_add_u32_e32 v206, -2, v192
	s_waitcnt vmcnt(19)
	v_add_f32_e32 v202, v203, v202
	v_mul_f32_e64 v203, |v202|, s81
	v_exp_f32_e32 v203, v203
	v_cndmask_b32_e32 v205, v205, v192, vcc
	s_waitcnt vmcnt(18)
	v_mul_f32_e32 v204, 0x3fb8aa3b, v204
	v_exp_f32_e32 v204, v204
	v_add_f32_e32 v203, 1.0, v203
	v_cmp_gt_f32_e32 vcc, s82, v203
	v_max_f32_e32 v202, 0, v202
	v_lshlrev_b32_e32 v205, 2, v205
	v_cndmask_b32_e64 v207, 0, 32, vcc
	v_ldexp_f32 v203, v203, v207
	v_log_f32_e32 v203, v203
	v_cndmask_b32_e32 v207, 0, v196, vcc
	s_waitcnt vmcnt(17)
	v_mul_f32_e32 v200, 0xbfb8aa3b, v200
	v_exp_f32_e32 v200, v200
	v_mul_f32_e32 v208, 0x3f317217, v203
	v_fma_f32 v208, v203, s83, -v208
	v_fmac_f32_e32 v208, 0x3377d1cf, v203
	v_fmac_f32_e32 v208, 0x3f317217, v203
	v_cmp_lt_f32_e64 vcc, |v203|, s97
	v_add_f32_e32 v200, 1.0, v200
	s_nop 0
	v_cndmask_b32_e32 v203, v203, v208, vcc
	v_sub_f32_e32 v203, v203, v207
	v_add_f32_e32 v202, v202, v203
	v_mul_f32_e64 v203, v202, -v204
	ds_bpermute_b32 v205, v205, v203
	v_cmp_lt_i32_e32 vcc, v206, v201
	v_add_u32_e32 v207, -4, v192
	s_waitcnt lgkmcnt(0)
	v_fma_f32 v202, v202, -v204, v205
	v_cndmask_b32_e32 v206, v206, v192, vcc
	v_cmp_eq_u32_e32 vcc, 0, v56
	v_lshlrev_b32_e32 v206, 2, v206
	v_add_u32_e32 v204, -8, v192
	v_cndmask_b32_e32 v202, v202, v203, vcc
	ds_bpermute_b32 v203, v206, v202
	v_cmp_lt_i32_e32 vcc, v207, v201
	s_waitcnt lgkmcnt(0)
	v_add_f32_e32 v203, v202, v203
	v_cndmask_b32_e32 v205, v207, v192, vcc
	v_cmp_gt_u32_e32 vcc, 2, v56
	v_lshlrev_b32_e32 v205, 2, v205
	s_nop 0
	v_cndmask_b32_e32 v202, v203, v202, vcc
	ds_bpermute_b32 v203, v205, v202
	v_cmp_lt_i32_e32 vcc, v204, v201
	v_add_u32_e32 v205, -16, v192
	s_waitcnt lgkmcnt(0)
	v_add_f32_e32 v203, v202, v203
	v_cndmask_b32_e32 v204, v204, v192, vcc
	v_cmp_gt_u32_e32 vcc, 4, v56
	v_lshlrev_b32_e32 v204, 2, v204
	s_nop 0
	v_cndmask_b32_e32 v202, v203, v202, vcc
	ds_bpermute_b32 v203, v204, v202
	v_cmp_lt_i32_e32 vcc, v205, v201
	v_subrev_u32_e32 v204, 32, v192
	s_waitcnt lgkmcnt(0)
	v_add_f32_e32 v203, v202, v203
	v_cndmask_b32_e32 v205, v205, v192, vcc
	v_cmp_gt_u32_e32 vcc, 8, v56
	v_lshlrev_b32_e32 v205, 2, v205
	s_nop 0
	v_cndmask_b32_e32 v202, v203, v202, vcc
	ds_bpermute_b32 v203, v205, v202
	v_cmp_lt_i32_e32 vcc, v204, v201
	s_waitcnt lgkmcnt(0)
	v_add_f32_e32 v203, v202, v203
	v_cndmask_b32_e32 v201, v204, v192, vcc
	v_cmp_gt_u32_e32 vcc, 16, v56
	v_lshlrev_b32_e32 v201, 2, v201
	v_rcp_f32_e32 v204, v200
	v_cndmask_b32_e32 v202, v203, v202, vcc
	ds_bpermute_b32 v201, v201, v202
	v_cmp_gt_u32_e32 vcc, 32, v56
	v_lshl_add_u32 v203, v56, 2, v63
	s_waitcnt lgkmcnt(0)
	v_add_f32_e32 v200, v202, v201
	v_cndmask_b32_e32 v201, v200, v202, vcc
	v_cmp_eq_u32_e32 vcc, 63, v56
	ds_write2st64_b32 v203, v201, v204 offset1:1
	s_and_saveexec_b64 s[6:7], vcc
	s_cbranch_execz .LBB0_419
	v_mul_f32_e32 v200, 0x3fb8aa3b, v200
	v_exp_f32_e32 v200, v200
	v_lshl_add_u64 v[202:203], v[40:41], 0, s[24:25]
	global_store_dword v[202:203], v200, off
; #define LAS __attribute__((address_space(3)))
; __device__ __forceinline__ float exp_f(float x) { return __builtin_amdgcn_exp2f(x * 1.4426950408889634f); }
; #define LBAR() do { asm volatile("s_waitcnt lgkmcnt(0)" ::: "memory"); __builtin_amdgcn_s_barrier(); asm volatile("" ::: "memory"); } while (0)
; __device__ __forceinline__ void prep_task(LAS unsigned char* lds, const PrepP& P, int task, int tid, int lane, int wave) {
;     ...
;     LBAR();
;     {
;         const int t = tid >> 3, seg = tid & 7;
;         const float beta = gcl[64 + t], gc = gcl[t], glc = gcl[63];
;         const float eg = exp_f(gc), et = exp_f(glc - gc);
;         const int tt = n * 64 + t;
;         const bf16_t* zr = P.z + (size_t)(row0 + t) * NZ + 4096 + h * 128 + seg * 16;
;         const LAS float* cw = (const LAS float*)(lds + 114688) + seg * 16;
;         u32x4 xz[3][2][4];
; #pragma unroll
;         for (int m = 0; m < 3; ++m)
; #pragma unroll
;             for (int hf = 0; hf < 2; ++hf)
; #pragma unroll
;                 for (int j = 0; j < 4; ++j) { const bool ok = tt - 3 + j >= 0; xz[m][hf][j] = *(const u32x4*)(zr + m * 1024 + hf * 8 + (ptrdiff_t)(ok ? j - 3 : 0) * NZ); if (!ok) xz[m][hf][j] = (u32x4){0u, 0u, 0u, 0u}; }
;         const int lo = t * PS + seg * 16;
;         float x[16], y[16];
;         { float o[8]; conv8(xz[2][0], cw + 256, o);
; #pragma unroll
;           for (int i = 0; i < 8; ++i) x[i] = o[i] * beta;
;           conv8(xz[2][1], cw + 256 + 8, o);
; #pragma unroll
;           for (int i = 0; i < 8; ++i) x[8 + i] = o[i] * beta; }
.LBB0_419:
	s_or_b64 exec, exec, s[6:7]
	s_mov_b64 vcc, s[98:99]
	s_mov_b64 s[6:7], s[100:101]
.Lp3_b0_skip:
	s_waitcnt lgkmcnt(0)
	s_barrier
	v_lshl_add_u32 v12, v26, 2, v63
	v_add_u32_e32 v14, 0x1b8fc, v58
	ds_read2st64_b32 v[24:25], v12 offset1:1
	ds_read_b32 v12, v14
	global_load_dwordx4 v[130:133], v[4:5], off offset:16
	global_load_dwordx4 v[134:137], v[8:9], off offset:16
	v_cmp_lt_i32_e64 s[10:11], -1, v27
	s_mov_b32 s14, 0x1c000
	s_waitcnt lgkmcnt(0)
	v_sub_f32_e32 v8, v12, v24
	global_load_dwordx4 v[4:7], v[6:7], off offset:16
	v_mul_f32_e32 v62, 0x3fb8aa3b, v8
	global_load_dwordx4 v[138:141], v[10:11], off offset:16
	global_load_dwordx4 v[12:15], v[28:29], off offset:16
	s_nop 0
	global_load_dwordx4 v[8:11], v[30:31], off offset:16
	global_load_dwordx4 v[142:145], v[32:33], off offset:16
	v_mul_f32_e32 v61, 0x3fb8aa3b, v24
	v_mul_lo_u32 v164, v26, s50
	v_add_u32_e32 v57, 0x11000, v58
	s_waitcnt vmcnt(20)
	v_cndmask_b32_e64 v30, 0, v71, s[6:7]
	v_cndmask_b32_e64 v33, 0, v70, s[6:7]
	v_cndmask_b32_e64 v35, 0, v69, s[6:7]
	v_cndmask_b32_e64 v37, 0, v68, s[6:7]
	s_waitcnt vmcnt(19)
	v_cndmask_b32_e32 v24, 0, v3, vcc
	v_cndmask_b32_e32 v27, 0, v2, vcc
	v_cndmask_b32_e64 v36, 0, v16, s[10:11]
	v_lshlrev_b32_e32 v16, 2, v60
	v_add3_u32 v31, v58, v16, s14
	v_cndmask_b32_e64 v29, 0, v19, s[10:11]
	s_waitcnt vmcnt(10)
	v_cndmask_b32_e32 v148, 0, v114, vcc
	s_waitcnt vmcnt(9)
	v_cndmask_b32_e64 v152, 0, v118, s[8:9]
	v_cndmask_b32_e64 v32, 0, v18, s[10:11]
	v_cndmask_b32_e64 v34, 0, v17, s[10:11]
	v_cndmask_b32_e32 v38, 0, v23, vcc
	v_cndmask_b32_e32 v49, 0, v22, vcc
	v_cndmask_b32_e32 v51, 0, v21, vcc
	v_cndmask_b32_e32 v53, 0, v20, vcc
	v_cndmask_b32_e64 v39, 0, v67, s[8:9]
	v_cndmask_b32_e64 v50, 0, v66, s[8:9]
	v_cndmask_b32_e64 v52, 0, v65, s[8:9]
	v_cndmask_b32_e64 v59, 0, v64, s[8:9]
	v_cndmask_b32_e32 v28, 0, v1, vcc
	v_cndmask_b32_e32 v85, 0, v75, vcc
	v_cndmask_b32_e32 v87, 0, v74, vcc
	v_cndmask_b32_e32 v90, 0, v73, vcc
	v_cndmask_b32_e32 v92, 0, v72, vcc
	v_cndmask_b32_e64 v86, 0, v79, s[8:9]
	v_cndmask_b32_e64 v88, 0, v78, s[8:9]
	v_cndmask_b32_e64 v91, 0, v77, s[8:9]
	v_cndmask_b32_e64 v93, 0, v76, s[8:9]
	v_cndmask_b32_e64 v1, 0, v83, s[6:7]
	v_cndmask_b32_e64 v79, 0, v82, s[6:7]
	v_cndmask_b32_e64 v83, 0, v80, s[6:7]
	v_cndmask_b32_e64 v78, 0, v97, s[10:11]
	v_cndmask_b32_e64 v80, 0, v96, s[10:11]
	v_cndmask_b32_e64 v82, 0, v95, s[10:11]
	v_cndmask_b32_e64 v84, 0, v94, s[10:11]
	v_cndmask_b32_e32 v65, 0, v101, vcc
	v_cndmask_b32_e32 v69, 0, v100, vcc
	v_cndmask_b32_e32 v74, 0, v99, vcc
	v_cndmask_b32_e32 v76, 0, v98, vcc
	v_cndmask_b32_e64 v64, 0, v105, s[8:9]
	v_cndmask_b32_e64 v68, 0, v104, s[8:9]
	v_cndmask_b32_e64 v75, 0, v103, s[8:9]
	v_cndmask_b32_e64 v77, 0, v102, s[8:9]
	v_cndmask_b32_e64 v3, 0, v109, s[6:7]
	v_cndmask_b32_e64 v67, 0, v108, s[6:7]
	v_cndmask_b32_e64 v70, 0, v107, s[6:7]
	v_cndmask_b32_e64 v72, 0, v106, s[6:7]
	v_cndmask_b32_e64 v2, 0, v113, s[10:11]
	v_cndmask_b32_e64 v66, 0, v112, s[10:11]
	v_cndmask_b32_e64 v71, 0, v111, s[10:11]
	v_cndmask_b32_e64 v73, 0, v110, s[10:11]
	v_cndmask_b32_e32 v89, 0, v117, vcc
	v_cndmask_b32_e32 v146, 0, v116, vcc
	v_cndmask_b32_e32 v147, 0, v115, vcc
	v_cndmask_b32_e64 v149, 0, v121, s[8:9]
	v_cndmask_b32_e64 v150, 0, v120, s[8:9]
	v_cndmask_b32_e64 v151, 0, v119, s[8:9]
	s_waitcnt vmcnt(8)
	v_cndmask_b32_e64 v156, 0, v125, s[6:7]
	v_cndmask_b32_e64 v157, 0, v124, s[6:7]
	v_cndmask_b32_e64 v158, 0, v123, s[6:7]
	v_cndmask_b32_e64 v159, 0, v122, s[6:7]
	s_waitcnt vmcnt(7)
	v_cndmask_b32_e64 v160, 0, v129, s[10:11]
	v_cndmask_b32_e64 v161, 0, v128, s[10:11]
	v_cndmask_b32_e64 v162, 0, v127, s[10:11]
	v_cndmask_b32_e64 v163, 0, v126, s[10:11]
	ds_read_b128 v[94:97], v31 offset:1024
	ds_read_b128 v[98:101], v31 offset:1040
	ds_read_b128 v[20:23], v31 offset:1056
	ds_read_b128 v[16:19], v31 offset:1072
	ds_read_b128 v[102:105], v31 offset:2560
	ds_read_b128 v[106:109], v31 offset:2576
	ds_read_b128 v[110:113], v31 offset:4096
	ds_read_b128 v[114:117], v31 offset:4112
	ds_read_b128 v[118:121], v31 offset:5632
	ds_read_b128 v[122:125], v31 offset:5648
	v_lshlrev_b32_e32 v127, 16, v152
	v_lshlrev_b32_e32 v126, 16, v148
	s_waitcnt lgkmcnt(9)
	v_mov_b32_e32 v128, v94
	s_waitcnt lgkmcnt(5)
	v_mov_b32_e32 v129, v102
	v_pk_mul_f32 v[126:127], v[128:129], v[126:127]
	v_mov_b32_e32 v102, v95
	v_add_f32_e32 v94, 0, v126
	v_add_f32_e32 v128, v94, v127
	v_and_b32_e32 v127, 0xffff0000, v152
	v_and_b32_e32 v126, 0xffff0000, v148
	v_pk_mul_f32 v[94:95], v[102:103], v[126:127]
	v_mov_b32_e32 v102, v96
	v_add_f32_e32 v94, 0, v94
	v_add_f32_e32 v126, v94, v95
	v_lshlrev_b32_e32 v95, 16, v151
	v_lshlrev_b32_e32 v94, 16, v147
	v_mov_b32_e32 v103, v104
	v_pk_mul_f32 v[94:95], v[102:103], v[94:95]
	v_mov_b32_e32 v104, v97
	v_add_f32_e32 v94, 0, v94
	v_add_f32_e32 v102, v94, v95
	v_and_b32_e32 v95, 0xffff0000, v151
	v_and_b32_e32 v94, 0xffff0000, v147
	v_pk_mul_f32 v[94:95], v[104:105], v[94:95]
	v_mov_b32_e32 v96, v98
	v_add_f32_e32 v94, 0, v94
	v_add_f32_e32 v103, v94, v95
	v_lshlrev_b32_e32 v95, 16, v150
	v_lshlrev_b32_e32 v94, 16, v146
	s_waitcnt lgkmcnt(4)
	v_mov_b32_e32 v97, v106
	v_pk_mul_f32 v[94:95], v[96:97], v[94:95]
	v_mov_b32_e32 v106, v99
	v_add_f32_e32 v94, 0, v94
	v_add_f32_e32 v98, v94, v95
	v_and_b32_e32 v95, 0xffff0000, v150
	v_and_b32_e32 v94, 0xffff0000, v146
	v_pk_mul_f32 v[94:95], v[106:107], v[94:95]
	v_mov_b32_e32 v96, v100
	v_add_f32_e32 v94, 0, v94
	v_add_f32_e32 v99, v94, v95
	v_lshlrev_b32_e32 v95, 16, v149
	v_lshlrev_b32_e32 v94, 16, v89
	v_mov_b32_e32 v97, v108
	v_pk_mul_f32 v[94:95], v[96:97], v[94:95]
	v_mov_b32_e32 v108, v101
	v_add_f32_e32 v94, 0, v94
	v_add_f32_e32 v100, v94, v95
	v_and_b32_e32 v95, 0xffff0000, v149
	v_and_b32_e32 v94, 0xffff0000, v89
	v_pk_mul_f32 v[94:95], v[108:109], v[94:95]
	s_waitcnt lgkmcnt(3)
; #define LAS __attribute__((address_space(3)))
; __device__ __forceinline__ float bflo(unsigned w) { return __uint_as_float(w << 16); }
; __device__ __forceinline__ float bfhi(unsigned w) { return __uint_as_float(w & 0xffff0000u); }
; __device__ __forceinline__ float silu_f(float x) { return x * rcp_f(1.f + exp_f(-x)); }
; __device__ __forceinline__ u32x4 pack8(const float* v) { u32x4 o; o.x = pk2(v[0], v[1]); o.y = pk2(v[2], v[3]); o.z = pk2(v[4], v[5]); o.w = pk2(v[6], v[7]); return o; }
; __device__ __forceinline__ void conv8(const u32x4 (&x)[4], const LAS float* w, float (&o)[8]) {
;     f32x4 wa[4], wb[4];
; #pragma unroll
;     for (int j = 0; j < 4; ++j) { wa[j] = *(const LAS f32x4*)(w + j * 384); wb[j] = *(const LAS f32x4*)(w + j * 384 + 4); }
; #pragma unroll
;     for (int i = 0; i < 8; ++i) o[i] = 0.f;
; #pragma unroll
;     for (int j = 0; j < 4; ++j) {
;         o[0] += wa[j].x * bflo(x[j].x); o[1] += wa[j].y * bfhi(x[j].x); o[2] += wa[j].z * bflo(x[j].y); o[3] += wa[j].w * bfhi(x[j].y);
;         o[4] += wb[j].x * bflo(x[j].z); o[5] += wb[j].y * bfhi(x[j].z); o[6] += wb[j].z * bflo(x[j].w); o[7] += wb[j].w * bfhi(x[j].w); }
; #pragma unroll
;     for (int i = 0; i < 8; ++i) o[i] = silu_f(o[i]);
; __device__ __forceinline__ void prep_task(LAS unsigned char* lds, const PrepP& P, int task, int tid, int lane, int wave) {
;     ...
;         { float o[8]; conv8(xz[2][0], cw + 256, o);
; #pragma unroll
;           for (int i = 0; i < 8; ++i) x[i] = o[i] * beta;
;           conv8(xz[2][1], cw + 256 + 8, o);
; #pragma unroll
;           for (int i = 0; i < 8; ++i) x[8 + i] = o[i] * beta; }
;         *(LAS u32x4*)(Vl + lo) = pack8(x); *(LAS u32x4*)(Vl + lo + 8) = pack8(x + 8);
	v_mov_b32_e32 v96, v110
	v_add_f32_e32 v89, 0, v94
	v_add_f32_e32 v89, v89, v95
	v_lshlrev_b32_e32 v94, 16, v159
	v_lshlrev_b32_e32 v95, 16, v163
	s_waitcnt lgkmcnt(1)
	v_mov_b32_e32 v97, v118
	v_pk_mul_f32 v[94:95], v[96:97], v[94:95]
	v_mov_b32_e32 v118, v111
	v_add_f32_e32 v94, v128, v94
	v_add_f32_e32 v101, v94, v95
	v_and_b32_e32 v95, 0xffff0000, v163
	v_and_b32_e32 v94, 0xffff0000, v159
	v_pk_mul_f32 v[94:95], v[118:119], v[94:95]
	v_mov_b32_e32 v96, v112
	v_add_f32_e32 v94, v126, v94
	v_add_f32_e32 v104, v94, v95
	v_lshlrev_b32_e32 v94, 16, v158
	v_lshlrev_b32_e32 v95, 16, v162
	v_mov_b32_e32 v97, v120
	v_pk_mul_f32 v[94:95], v[96:97], v[94:95]
	v_mov_b32_e32 v120, v113
	v_add_f32_e32 v94, v102, v94
	v_add_f32_e32 v102, v94, v95
	v_and_b32_e32 v95, 0xffff0000, v162
	v_and_b32_e32 v94, 0xffff0000, v158
	v_pk_mul_f32 v[94:95], v[120:121], v[94:95]
	v_mov_b32_e32 v96, v114
	v_add_f32_e32 v94, v103, v94
	v_add_f32_e32 v103, v94, v95
	v_lshlrev_b32_e32 v94, 16, v157
	v_lshlrev_b32_e32 v95, 16, v161
	s_waitcnt lgkmcnt(0)
	v_mov_b32_e32 v97, v122
	v_pk_mul_f32 v[94:95], v[96:97], v[94:95]
	v_mov_b32_e32 v122, v115
	v_add_f32_e32 v94, v98, v94
	v_add_f32_e32 v98, v94, v95
	v_and_b32_e32 v95, 0xffff0000, v161
	v_and_b32_e32 v94, 0xffff0000, v157
	v_pk_mul_f32 v[94:95], v[122:123], v[94:95]
	v_mov_b32_e32 v96, v116
	v_add_f32_e32 v94, v99, v94
	v_add_f32_e32 v99, v94, v95
	v_lshlrev_b32_e32 v94, 16, v156
	v_lshlrev_b32_e32 v95, 16, v160
	v_mov_b32_e32 v97, v124
	v_pk_mul_f32 v[94:95], v[96:97], v[94:95]
	v_mul_f32_e32 v97, 0xbfb8aa3b, v101
	v_exp_f32_e32 v97, v97
	v_add_f32_e32 v94, v100, v94
	v_add_f32_e32 v96, v94, v95
	v_and_b32_e32 v95, 0xffff0000, v160
	v_and_b32_e32 v94, 0xffff0000, v156
	v_mov_b32_e32 v124, v117
	v_pk_mul_f32 v[94:95], v[124:125], v[94:95]
	v_mul_f32_e32 v100, 0xbfb8aa3b, v103
	v_add_f32_e32 v89, v89, v94
	v_add_f32_e32 v94, 1.0, v97
	v_mul_f32_e32 v97, 0xbfb8aa3b, v102
	v_add_f32_e32 v89, v89, v95
	v_mul_f32_e32 v95, 0xbfb8aa3b, v104
	v_exp_f32_e32 v97, v97
	v_exp_f32_e32 v100, v100
	v_exp_f32_e32 v95, v95
	v_rcp_f32_e32 v94, v94
	v_add_f32_e32 v97, 1.0, v97
	v_add_f32_e32 v100, 1.0, v100
	v_add_f32_e32 v95, 1.0, v95
	v_rcp_f32_e32 v97, v97
	v_rcp_f32_e32 v100, v100
	v_rcp_f32_e32 v95, v95
	v_mul_f32_e32 v94, v101, v94
	v_mul_f32_e32 v97, v102, v97
	v_mul_f32_e32 v101, 0xbfb8aa3b, v98
	v_mul_f32_e32 v102, 0xbfb8aa3b, v99
	v_mul_f32_e32 v100, v103, v100
	v_mul_f32_e32 v103, 0xbfb8aa3b, v96
	v_mul_f32_e32 v95, v104, v95
	v_exp_f32_e32 v101, v101
	v_exp_f32_e32 v102, v102
	v_exp_f32_e32 v103, v103
	v_mul_f32_e32 v104, 0xbfb8aa3b, v89
	v_exp_f32_e32 v104, v104
	v_add_f32_e32 v101, 1.0, v101
	v_add_f32_e32 v102, 1.0, v102
	v_add_f32_e32 v103, 1.0, v103
	v_rcp_f32_e32 v101, v101
	v_rcp_f32_e32 v102, v102
	v_rcp_f32_e32 v103, v103
	v_add_f32_e32 v104, 1.0, v104
	v_rcp_f32_e32 v104, v104
	s_waitcnt vmcnt(6)
	v_cndmask_b32_e32 v130, 0, v130, vcc
	s_waitcnt vmcnt(5)
	v_cndmask_b32_e64 v134, 0, v134, s[8:9]
	v_mul_f32_e32 v98, v98, v101
	v_mul_f32_e32 v99, v99, v102
	v_mul_f32_e32 v96, v96, v103
	v_mul_f32_e32 v89, v89, v104
	v_mul_f32_e32 v122, v25, v94
	v_mul_f32_e32 v123, v25, v95
	v_mul_f32_e32 v124, v25, v97
	v_mul_f32_e32 v125, v25, v100
	v_mul_f32_e32 v126, v25, v98
	v_mul_f32_e32 v127, v25, v99
	v_mul_f32_e32 v128, v25, v96
	ds_read_b128 v[94:97], v31 offset:2592
	ds_read_b128 v[98:101], v31 offset:2608
	ds_read_b128 v[102:105], v31 offset:4128
	ds_read_b128 v[106:109], v31 offset:4144
	ds_read_b128 v[110:113], v31 offset:5664
	ds_read_b128 v[114:117], v31 offset:5680
	v_lshlrev_b32_e32 v119, 16, v134
	v_lshlrev_b32_e32 v118, 16, v130
	v_mov_b32_e32 v120, v20
	s_waitcnt lgkmcnt(5)
	v_mov_b32_e32 v121, v94
	v_pk_mul_f32 v[118:119], v[120:121], v[118:119]
	v_mov_b32_e32 v94, v21
	v_add_f32_e32 v20, 0, v118
	v_add_f32_e32 v120, v20, v119
	v_and_b32_e32 v119, 0xffff0000, v134
	v_and_b32_e32 v118, 0xffff0000, v130
	v_pk_mul_f32 v[20:21], v[94:95], v[118:119]
	v_cndmask_b32_e32 v131, 0, v131, vcc
	v_cndmask_b32_e64 v135, 0, v135, s[8:9]
	v_add_f32_e32 v20, 0, v20
	v_add_f32_e32 v118, v20, v21
	v_lshlrev_b32_e32 v21, 16, v135
	v_lshlrev_b32_e32 v20, 16, v131
	v_mov_b32_e32 v94, v22
	v_mov_b32_e32 v95, v96
	v_pk_mul_f32 v[20:21], v[94:95], v[20:21]
	v_mov_b32_e32 v96, v23
	v_add_f32_e32 v20, 0, v20
	v_add_f32_e32 v94, v20, v21
	v_and_b32_e32 v21, 0xffff0000, v135
	v_and_b32_e32 v20, 0xffff0000, v131
	v_pk_mul_f32 v[20:21], v[96:97], v[20:21]
	v_cndmask_b32_e32 v132, 0, v132, vcc
	v_cndmask_b32_e64 v136, 0, v136, s[8:9]
	v_add_f32_e32 v20, 0, v20
	v_add_f32_e32 v95, v20, v21
	v_lshlrev_b32_e32 v21, 16, v136
	v_lshlrev_b32_e32 v20, 16, v132
	v_mov_b32_e32 v22, v16
	s_waitcnt lgkmcnt(4)
	v_mov_b32_e32 v23, v98
	v_pk_mul_f32 v[20:21], v[22:23], v[20:21]
	v_mov_b32_e32 v98, v17
	v_add_f32_e32 v16, 0, v20
	v_add_f32_e32 v22, v16, v21
	v_and_b32_e32 v21, 0xffff0000, v136
	v_and_b32_e32 v20, 0xffff0000, v132
	v_pk_mul_f32 v[16:17], v[98:99], v[20:21]
	v_cndmask_b32_e32 v133, 0, v133, vcc
	v_cndmask_b32_e64 v137, 0, v137, s[8:9]
	v_add_f32_e32 v16, 0, v16
	v_add_f32_e32 v23, v16, v17
	v_lshlrev_b32_e32 v17, 16, v137
	v_lshlrev_b32_e32 v16, 16, v133
	v_mov_b32_e32 v20, v18
	v_mov_b32_e32 v21, v100
	v_pk_mul_f32 v[16:17], v[20:21], v[16:17]
	v_mov_b32_e32 v100, v19
	v_add_f32_e32 v16, 0, v16
	v_add_f32_e32 v20, v16, v17
	v_and_b32_e32 v17, 0xffff0000, v137
	v_and_b32_e32 v16, 0xffff0000, v133
	v_pk_mul_f32 v[16:17], v[100:101], v[16:17]
	s_waitcnt vmcnt(3)
	v_cndmask_b32_e64 v138, 0, v138, s[6:7]
	s_waitcnt vmcnt(0)
	v_cndmask_b32_e64 v142, 0, v142, s[10:11]
	v_add_f32_e32 v16, 0, v16
	v_add_f32_e32 v21, v16, v17
	v_lshlrev_b32_e32 v17, 16, v142
	v_lshlrev_b32_e32 v16, 16, v138
	s_waitcnt lgkmcnt(3)
; #define LAS __attribute__((address_space(3)))
; __device__ __forceinline__ float bflo(unsigned w) { return __uint_as_float(w << 16); }
; __device__ __forceinline__ float bfhi(unsigned w) { return __uint_as_float(w & 0xffff0000u); }
; __device__ __forceinline__ float silu_f(float x) { return x * rcp_f(1.f + exp_f(-x)); }
; __device__ __forceinline__ u32x4 pack8(const float* v) { u32x4 o; o.x = pk2(v[0], v[1]); o.y = pk2(v[2], v[3]); o.z = pk2(v[4], v[5]); o.w = pk2(v[6], v[7]); return o; }
; __device__ __forceinline__ void conv8(const u32x4 (&x)[4], const LAS float* w, float (&o)[8]) {
;     f32x4 wa[4], wb[4];
; #pragma unroll
;     for (int j = 0; j < 4; ++j) { wa[j] = *(const LAS f32x4*)(w + j * 384); wb[j] = *(const LAS f32x4*)(w + j * 384 + 4); }
; #pragma unroll
;     for (int i = 0; i < 8; ++i) o[i] = 0.f;
; #pragma unroll
;     for (int j = 0; j < 4; ++j) {
;         o[0] += wa[j].x * bflo(x[j].x); o[1] += wa[j].y * bfhi(x[j].x); o[2] += wa[j].z * bflo(x[j].y); o[3] += wa[j].w * bfhi(x[j].y);
;         o[4] += wb[j].x * bflo(x[j].z); o[5] += wb[j].y * bfhi(x[j].z); o[6] += wb[j].z * bflo(x[j].w); o[7] += wb[j].w * bfhi(x[j].w); }
; #pragma unroll
;     for (int i = 0; i < 8; ++i) o[i] = silu_f(o[i]);
; __device__ __forceinline__ void prep_task(LAS unsigned char* lds, const PrepP& P, int task, int tid, int lane, int wave) {
;     ...
;           conv8(xz[2][1], cw + 256 + 8, o);
; #pragma unroll
;           for (int i = 0; i < 8; ++i) x[8 + i] = o[i] * beta; }
;         *(LAS u32x4*)(Vl + lo) = pack8(x); *(LAS u32x4*)(Vl + lo + 8) = pack8(x + 8);
;         asm volatile("" ::: "memory");
;         { float o[8]; conv8(xz[1][0], cw + 128, o);
; #pragma unroll
;           for (int i = 0; i < 8; ++i) x[i] = o[i];
;           conv8(xz[1][1], cw + 128 + 8, o);
	v_mov_b32_e32 v18, v102
	s_waitcnt lgkmcnt(1)
	v_mov_b32_e32 v19, v110
	v_pk_mul_f32 v[16:17], v[18:19], v[16:17]
	v_mov_b32_e32 v110, v103
	v_add_f32_e32 v16, v120, v16
	v_add_f32_e32 v96, v16, v17
	v_and_b32_e32 v17, 0xffff0000, v142
	v_and_b32_e32 v16, 0xffff0000, v138
	v_pk_mul_f32 v[16:17], v[110:111], v[16:17]
	v_cndmask_b32_e64 v139, 0, v139, s[6:7]
	v_cndmask_b32_e64 v143, 0, v143, s[10:11]
	v_add_f32_e32 v16, v118, v16
	v_add_f32_e32 v97, v16, v17
	v_lshlrev_b32_e32 v17, 16, v143
	v_lshlrev_b32_e32 v16, 16, v139
	v_mov_b32_e32 v18, v104
	v_mov_b32_e32 v19, v112
	v_pk_mul_f32 v[16:17], v[18:19], v[16:17]
	v_mov_b32_e32 v112, v105
	v_add_f32_e32 v16, v94, v16
	v_add_f32_e32 v94, v16, v17
	v_and_b32_e32 v17, 0xffff0000, v143
	v_and_b32_e32 v16, 0xffff0000, v139
	v_pk_mul_f32 v[16:17], v[112:113], v[16:17]
	v_cndmask_b32_e64 v140, 0, v140, s[6:7]
	v_cndmask_b32_e64 v144, 0, v144, s[10:11]
	v_add_f32_e32 v16, v95, v16
	v_add_f32_e32 v95, v16, v17
	v_lshlrev_b32_e32 v17, 16, v144
	v_lshlrev_b32_e32 v16, 16, v140
	v_mov_b32_e32 v18, v106
	s_waitcnt lgkmcnt(0)
	v_mov_b32_e32 v19, v114
	v_pk_mul_f32 v[16:17], v[18:19], v[16:17]
	v_mov_b32_e32 v114, v107
	v_add_f32_e32 v16, v22, v16
	v_add_f32_e32 v22, v16, v17
	v_and_b32_e32 v17, 0xffff0000, v144
	v_and_b32_e32 v16, 0xffff0000, v140
	v_pk_mul_f32 v[16:17], v[114:115], v[16:17]
	v_cndmask_b32_e64 v141, 0, v141, s[6:7]
	v_cndmask_b32_e64 v145, 0, v145, s[10:11]
	v_add_f32_e32 v16, v23, v16
	v_add_f32_e32 v23, v16, v17
	v_lshlrev_b32_e32 v17, 16, v145
	v_lshlrev_b32_e32 v16, 16, v141
	v_mov_b32_e32 v18, v108
	v_mov_b32_e32 v19, v116
	v_pk_mul_f32 v[16:17], v[18:19], v[16:17]
	v_mul_f32_e32 v19, 0xbfb8aa3b, v96
	v_add_f32_e32 v16, v20, v16
	v_exp_f32_e32 v19, v19
	v_add_f32_e32 v18, v16, v17
	v_and_b32_e32 v17, 0xffff0000, v145
	v_and_b32_e32 v16, 0xffff0000, v141
	v_mov_b32_e32 v116, v109
	v_pk_mul_f32 v[16:17], v[116:117], v[16:17]
	v_mul_f32_e32 v20, 0xbfb8aa3b, v94
	v_add_f32_e32 v16, v21, v16
	v_add_f32_e32 v16, v16, v17
	v_add_f32_e32 v17, 1.0, v19
	v_mul_f32_e32 v19, 0xbfb8aa3b, v97
	v_mul_f32_e32 v21, 0xbfb8aa3b, v95
	v_exp_f32_e32 v19, v19
	v_rcp_f32_e32 v17, v17
	v_exp_f32_e32 v21, v21
	v_exp_f32_e32 v20, v20
	v_add_f32_e32 v19, 1.0, v19
	v_mul_f32_e32 v17, v96, v17
	v_add_f32_e32 v21, 1.0, v21
	v_mul_f32_e32 v96, 0xbfb8aa3b, v23
	v_rcp_f32_e32 v19, v19
	v_add_f32_e32 v20, 1.0, v20
	v_rcp_f32_e32 v21, v21
	v_exp_f32_e32 v96, v96
	v_rcp_f32_e32 v20, v20
	v_mul_f32_e32 v19, v97, v19
	v_mul_f32_e32 v21, v95, v21
	v_add_f32_e32 v95, 1.0, v96
	v_mul_f32_e32 v96, 0xbfb8aa3b, v18
	v_mul_f32_e32 v97, 0xbfb8aa3b, v16
	v_mul_f32_e32 v20, v94, v20
	v_mul_f32_e32 v94, 0xbfb8aa3b, v22
	v_exp_f32_e32 v96, v96
	v_exp_f32_e32 v97, v97
	v_exp_f32_e32 v94, v94
	v_rcp_f32_e32 v95, v95
	v_add_f32_e32 v96, 1.0, v96
	v_add_f32_e32 v97, 1.0, v97
	v_add_f32_e32 v94, 1.0, v94
	v_rcp_f32_e32 v96, v96
	v_rcp_f32_e32 v97, v97
	v_rcp_f32_e32 v94, v94
	v_mul_f32_e32 v89, v25, v89
	v_mul_f32_e32 v23, v23, v95
	v_mul_f32_e32 v18, v18, v96
	v_mul_f32_e32 v16, v16, v97
	v_mul_f32_e32 v95, v25, v19
	v_cvt_pk_bf16_f32 v19, v128, v89
	v_add_lshl_u32 v89, v164, v60, 1
	v_mul_f32_e32 v22, v22, v94
	v_mul_f32_e32 v94, v25, v17
	v_mul_f32_e32 v96, v25, v18
	v_mul_f32_e32 v97, v25, v16
	v_cvt_pk_bf16_f32 v16, v122, v123
	v_cvt_pk_bf16_f32 v17, v124, v125
	v_cvt_pk_bf16_f32 v18, v126, v127
	v_add_u32_e32 v60, v58, v89
	v_mul_f32_e32 v20, v25, v20
	v_mul_f32_e32 v21, v25, v21
	v_mul_f32_e32 v22, v25, v22
	v_mul_f32_e32 v23, v25, v23
	ds_write_b128 v60, v[16:19] offset:34816
	v_cvt_pk_bf16_f32 v16, v94, v95
	v_cvt_pk_bf16_f32 v17, v20, v21
	v_cvt_pk_bf16_f32 v18, v22, v23
	v_cvt_pk_bf16_f32 v19, v96, v97
	ds_write_b128 v60, v[16:19] offset:34832
	ds_read_b128 v[94:97], v31 offset:512
	ds_read_b128 v[98:101], v31 offset:528
	ds_read_b128 v[20:23], v31 offset:544
	ds_read_b128 v[16:19], v31 offset:560
	ds_read_b128 v[102:105], v31 offset:2048
	ds_read_b128 v[106:109], v31 offset:2064
	ds_read_b128 v[110:113], v31 offset:3584
	ds_read_b128 v[114:117], v31 offset:3600
	ds_read_b128 v[118:121], v31 offset:5120
	ds_read_b128 v[122:125], v31 offset:5136
	v_lshlrev_b32_e32 v127, 16, v93
	v_lshlrev_b32_e32 v126, 16, v92
	s_waitcnt lgkmcnt(9)
	v_mov_b32_e32 v128, v94
	s_waitcnt lgkmcnt(5)
	v_mov_b32_e32 v129, v102
	v_and_b32_e32 v93, 0xffff0000, v93
	v_and_b32_e32 v92, 0xffff0000, v92
	v_mov_b32_e32 v102, v95
	v_pk_mul_f32 v[126:127], v[128:129], v[126:127]
	v_pk_mul_f32 v[92:93], v[102:103], v[92:93]
	v_add_f32_e32 v94, 0, v126
	v_add_f32_e32 v92, 0, v92
	v_add_f32_e32 v126, v94, v127
	v_add_f32_e32 v102, v92, v93
	v_lshlrev_b32_e32 v93, 16, v91
	v_lshlrev_b32_e32 v92, 16, v90
	v_mov_b32_e32 v94, v96
	v_mov_b32_e32 v95, v104
	v_and_b32_e32 v91, 0xffff0000, v91
	v_and_b32_e32 v90, 0xffff0000, v90
	v_mov_b32_e32 v104, v97
	v_pk_mul_f32 v[92:93], v[94:95], v[92:93]
	v_pk_mul_f32 v[90:91], v[104:105], v[90:91]
	v_add_f32_e32 v92, 0, v92
	v_add_f32_e32 v90, 0, v90
	v_add_f32_e32 v94, v92, v93
	v_add_f32_e32 v95, v90, v91
	v_lshlrev_b32_e32 v91, 16, v88
	v_lshlrev_b32_e32 v90, 16, v87
	v_mov_b32_e32 v92, v98
	s_waitcnt lgkmcnt(4)
	v_mov_b32_e32 v93, v106
	v_pk_mul_f32 v[90:91], v[92:93], v[90:91]
	v_mov_b32_e32 v106, v99
	v_add_f32_e32 v90, 0, v90
	v_add_f32_e32 v96, v90, v91
	v_and_b32_e32 v91, 0xffff0000, v88
	v_and_b32_e32 v90, 0xffff0000, v87
	v_pk_mul_f32 v[90:91], v[106:107], v[90:91]
	v_mov_b32_e32 v92, v100
	v_add_f32_e32 v87, 0, v90
	v_add_f32_e32 v88, v87, v91
	v_lshlrev_b32_e32 v91, 16, v86
	v_lshlrev_b32_e32 v90, 16, v85
	v_mov_b32_e32 v93, v108
	v_pk_mul_f32 v[90:91], v[92:93], v[90:91]
	v_mov_b32_e32 v108, v101
	v_add_f32_e32 v87, 0, v90
	v_add_f32_e32 v92, v87, v91
	v_and_b32_e32 v87, 0xffff0000, v86
	v_and_b32_e32 v86, 0xffff0000, v85
	v_pk_mul_f32 v[86:87], v[108:109], v[86:87]
	s_waitcnt lgkmcnt(3)
; #define LAS __attribute__((address_space(3)))
; __device__ __forceinline__ float bflo(unsigned w) { return __uint_as_float(w << 16); }
; __device__ __forceinline__ float bfhi(unsigned w) { return __uint_as_float(w & 0xffff0000u); }
; __device__ __forceinline__ float rsq_f(float x) { return __builtin_amdgcn_rsqf(x); }
; __device__ __forceinline__ float silu_f(float x) { return x * rcp_f(1.f + exp_f(-x)); }
; __device__ __forceinline__ void conv8(const u32x4 (&x)[4], const LAS float* w, float (&o)[8]) {
;     f32x4 wa[4], wb[4];
; #pragma unroll
;     for (int j = 0; j < 4; ++j) { wa[j] = *(const LAS f32x4*)(w + j * 384); wb[j] = *(const LAS f32x4*)(w + j * 384 + 4); }
; #pragma unroll
;     for (int i = 0; i < 8; ++i) o[i] = 0.f;
; #pragma unroll
;     for (int j = 0; j < 4; ++j) {
;         o[0] += wa[j].x * bflo(x[j].x); o[1] += wa[j].y * bfhi(x[j].x); o[2] += wa[j].z * bflo(x[j].y); o[3] += wa[j].w * bfhi(x[j].y);
;         o[4] += wb[j].x * bflo(x[j].z); o[5] += wb[j].y * bfhi(x[j].z); o[6] += wb[j].z * bflo(x[j].w); o[7] += wb[j].w * bfhi(x[j].w); }
; #pragma unroll
;     for (int i = 0; i < 8; ++i) o[i] = silu_f(o[i]);
; __device__ __forceinline__ void prep_task(LAS unsigned char* lds, const PrepP& P, int task, int tid, int lane, int wave) {
;     ...
;         { float o[8]; conv8(xz[1][0], cw + 128, o);
; #pragma unroll
;           for (int i = 0; i < 8; ++i) x[i] = o[i];
;           conv8(xz[1][1], cw + 128 + 8, o);
; #pragma unroll
;           for (int i = 0; i < 8; ++i) x[8 + i] = o[i]; }
;         { float sk = 0.f;
; #pragma unroll
;           for (int i = 0; i < 16; ++i) sk += x[i] * x[i];
;           sk += __shfl_xor(sk, 1); sk += __shfl_xor(sk, 2); sk += __shfl_xor(sk, 4);
;           const float rk = rsq_f(sk + EPS);
	v_mov_b32_e32 v90, v110
	v_add_f32_e32 v85, 0, v86
	v_add_f32_e32 v93, v85, v87
	v_lshlrev_b32_e32 v87, 16, v84
	v_lshlrev_b32_e32 v86, 16, v83
	s_waitcnt lgkmcnt(1)
	v_mov_b32_e32 v91, v118
	v_pk_mul_f32 v[86:87], v[90:91], v[86:87]
	v_mov_b32_e32 v118, v111
	v_add_f32_e32 v85, v126, v86
	v_add_f32_e32 v90, v85, v87
	v_and_b32_e32 v85, 0xffff0000, v84
	v_and_b32_e32 v84, 0xffff0000, v83
	v_pk_mul_f32 v[84:85], v[118:119], v[84:85]
	v_cndmask_b32_e64 v81, 0, v81, s[6:7]
	v_add_f32_e32 v83, v102, v84
	v_add_f32_e32 v91, v83, v85
	v_lshlrev_b32_e32 v85, 16, v82
	v_lshlrev_b32_e32 v84, 16, v81
	v_mov_b32_e32 v86, v112
	v_mov_b32_e32 v87, v120
	v_pk_mul_f32 v[84:85], v[86:87], v[84:85]
	v_mov_b32_e32 v120, v113
	v_add_f32_e32 v83, v94, v84
	v_add_f32_e32 v86, v83, v85
	v_and_b32_e32 v83, 0xffff0000, v82
	v_and_b32_e32 v82, 0xffff0000, v81
	v_pk_mul_f32 v[82:83], v[120:121], v[82:83]
	v_mov_b32_e32 v84, v114
	v_add_f32_e32 v81, v95, v82
	v_add_f32_e32 v87, v81, v83
	v_lshlrev_b32_e32 v83, 16, v80
	v_lshlrev_b32_e32 v82, 16, v79
	s_waitcnt lgkmcnt(0)
	v_mov_b32_e32 v85, v122
	v_pk_mul_f32 v[82:83], v[84:85], v[82:83]
	v_mov_b32_e32 v122, v115
	v_add_f32_e32 v81, v96, v82
	v_add_f32_e32 v84, v81, v83
	v_and_b32_e32 v81, 0xffff0000, v80
	v_and_b32_e32 v80, 0xffff0000, v79
	v_pk_mul_f32 v[80:81], v[122:123], v[80:81]
	v_mov_b32_e32 v82, v116
	v_add_f32_e32 v79, v88, v80
	v_add_f32_e32 v85, v79, v81
	v_lshlrev_b32_e32 v81, 16, v78
	v_lshlrev_b32_e32 v80, 16, v1
	v_mov_b32_e32 v83, v124
	v_pk_mul_f32 v[80:81], v[82:83], v[80:81]
	v_mov_b32_e32 v124, v117
	v_add_f32_e32 v79, v92, v80
	v_add_f32_e32 v80, v79, v81
	v_and_b32_e32 v79, 0xffff0000, v78
	v_and_b32_e32 v78, 0xffff0000, v1
	v_pk_mul_f32 v[78:79], v[124:125], v[78:79]
	v_mul_f32_e32 v1, 0xbfb8aa3b, v90
	v_add_f32_e32 v78, v93, v78
	v_add_f32_e32 v78, v78, v79
	v_mul_f32_e32 v79, 0xbfb8aa3b, v91
	v_mul_f32_e32 v81, 0xbfb8aa3b, v86
	v_exp_f32_e32 v1, v1
	v_exp_f32_e32 v79, v79
	v_exp_f32_e32 v81, v81
	v_mul_f32_e32 v82, 0xbfb8aa3b, v87
	v_add_f32_e32 v1, 1.0, v1
	v_add_f32_e32 v79, 1.0, v79
	v_add_f32_e32 v81, 1.0, v81
	v_rcp_f32_e32 v1, v1
	v_rcp_f32_e32 v79, v79
	v_rcp_f32_e32 v81, v81
	v_exp_f32_e32 v82, v82
	v_mul_f32_e32 v88, v90, v1
	v_mul_f32_e32 v108, v91, v79
	v_mul_f32_e32 v109, v86, v81
	v_add_f32_e32 v1, 1.0, v82
	v_mul_f32_e32 v79, 0xbfb8aa3b, v84
	v_mul_f32_e32 v81, 0xbfb8aa3b, v85
	v_rcp_f32_e32 v1, v1
	v_exp_f32_e32 v79, v79
	v_exp_f32_e32 v81, v81
	v_mul_f32_e32 v82, 0xbfb8aa3b, v78
	v_mul_f32_e32 v110, v87, v1
	v_add_f32_e32 v1, 1.0, v79
	v_add_f32_e32 v79, 1.0, v81
	v_mul_f32_e32 v81, 0xbfb8aa3b, v80
	v_exp_f32_e32 v81, v81
	v_exp_f32_e32 v82, v82
	v_rcp_f32_e32 v1, v1
	v_rcp_f32_e32 v79, v79
	v_add_f32_e32 v81, 1.0, v81
	v_add_f32_e32 v82, 1.0, v82
	v_rcp_f32_e32 v81, v81
	v_rcp_f32_e32 v82, v82
	v_mul_f32_e32 v111, v84, v1
	v_mul_f32_e32 v112, v85, v79
	v_mul_f32_e32 v1, v80, v81
	v_mul_f32_e32 v113, v78, v82
	ds_read_b128 v[78:81], v31 offset:2080
	ds_read_b128 v[82:85], v31 offset:2096
	ds_read_b128 v[90:93], v31 offset:3616
	ds_read_b128 v[94:97], v31 offset:3632
	ds_read_b128 v[98:101], v31 offset:5152
	ds_read_b128 v[102:105], v31 offset:5168
	v_lshlrev_b32_e32 v87, 16, v77
	v_lshlrev_b32_e32 v86, 16, v76
	v_mov_b32_e32 v106, v20
	s_waitcnt lgkmcnt(5)
	v_mov_b32_e32 v107, v78
	v_pk_mul_f32 v[86:87], v[106:107], v[86:87]
	v_and_b32_e32 v77, 0xffff0000, v77
	v_add_f32_e32 v20, 0, v86
	v_and_b32_e32 v76, 0xffff0000, v76
	v_mov_b32_e32 v78, v21
	v_add_f32_e32 v86, v20, v87
	v_pk_mul_f32 v[20:21], v[78:79], v[76:77]
	v_mov_b32_e32 v76, v22
	v_add_f32_e32 v20, 0, v20
	v_add_f32_e32 v78, v20, v21
	v_lshlrev_b32_e32 v21, 16, v75
	v_lshlrev_b32_e32 v20, 16, v74
	v_mov_b32_e32 v77, v80
	v_and_b32_e32 v75, 0xffff0000, v75
	v_and_b32_e32 v74, 0xffff0000, v74
	v_mov_b32_e32 v80, v23
	v_pk_mul_f32 v[20:21], v[76:77], v[20:21]
	v_pk_mul_f32 v[22:23], v[80:81], v[74:75]
	v_lshlrev_b32_e32 v75, 16, v73
	v_lshlrev_b32_e32 v74, 16, v72
	s_waitcnt lgkmcnt(3)
	v_mov_b32_e32 v76, v90
	s_waitcnt lgkmcnt(1)
	v_mov_b32_e32 v77, v98
	v_and_b32_e32 v73, 0xffff0000, v73
	v_and_b32_e32 v72, 0xffff0000, v72
	v_mov_b32_e32 v98, v91
	v_pk_mul_f32 v[74:75], v[76:77], v[74:75]
	v_pk_mul_f32 v[72:73], v[98:99], v[72:73]
	v_add_f32_e32 v74, v86, v74
	v_add_f32_e32 v72, v78, v72
	v_add_f32_e32 v76, v74, v75
	v_add_f32_e32 v77, v72, v73
	v_lshlrev_b32_e32 v73, 16, v71
	v_lshlrev_b32_e32 v72, 16, v70
	v_mov_b32_e32 v74, v92
	v_mov_b32_e32 v75, v100
	v_pk_mul_f32 v[72:73], v[74:75], v[72:73]
	v_mul_f32_e32 v74, 0xbfb8aa3b, v76
	v_mul_f32_e32 v75, 0xbfb8aa3b, v77
	v_exp_f32_e32 v74, v74
	v_exp_f32_e32 v75, v75
	v_and_b32_e32 v71, 0xffff0000, v71
	v_and_b32_e32 v70, 0xffff0000, v70
	v_add_f32_e32 v74, 1.0, v74
	v_add_f32_e32 v75, 1.0, v75
	v_rcp_f32_e32 v74, v74
	v_rcp_f32_e32 v75, v75
	v_mov_b32_e32 v100, v93
	v_pk_mul_f32 v[70:71], v[100:101], v[70:71]
	v_mul_f32_e32 v76, v76, v74
	v_mul_f32_e32 v77, v77, v75
	v_mov_b32_e32 v74, v22
	v_mov_b32_e32 v75, v20
	v_pk_add_f32 v[74:75], v[74:75], 0 op_sel_hi:[1,0]
	v_mov_b32_e32 v20, v23
	v_pk_add_f32 v[20:21], v[74:75], v[20:21]
	v_mov_b32_e32 v22, v70
	v_mov_b32_e32 v23, v72
	v_pk_add_f32 v[20:21], v[20:21], v[22:23]
	v_mov_b32_e32 v72, v71
	v_pk_add_f32 v[20:21], v[20:21], v[72:73]
	v_mul_f32_e32 v78, v108, v108
	v_mul_f32_e32 v22, 0xbfb8aa3b, v21
	v_exp_f32_e32 v22, v22
	v_mul_f32_e32 v23, 0xbfb8aa3b, v20
	v_exp_f32_e32 v70, v23
	v_fmac_f32_e32 v78, v88, v88
	v_add_f32_e32 v22, 1.0, v22
	v_rcp_f32_e32 v23, v22
	v_add_f32_e32 v22, 1.0, v70
	v_and_b32_e32 v71, 0xffff0000, v69
	v_lshlrev_b32_e32 v70, 16, v69
	v_fmac_f32_e32 v78, v109, v109
	v_pk_fma_f32 v[16:17], v[16:17], v[70:71], 0 op_sel_hi:[1,1,0]
	v_and_b32_e32 v69, 0xffff0000, v68
	v_lshlrev_b32_e32 v68, 16, v68
	v_fmac_f32_e32 v78, v110, v110
	v_pk_fma_f32 v[16:17], v[82:83], v[68:69], v[16:17]
	v_and_b32_e32 v69, 0xffff0000, v67
	v_lshlrev_b32_e32 v68, 16, v67
	v_fmac_f32_e32 v78, v111, v111
	v_rcp_f32_e32 v22, v22
	v_pk_fma_f32 v[16:17], v[94:95], v[68:69], v[16:17]
	v_and_b32_e32 v67, 0xffff0000, v66
	v_lshlrev_b32_e32 v66, 16, v66
	v_fmac_f32_e32 v78, v112, v112
	s_waitcnt lgkmcnt(0)
; #define LAS __attribute__((address_space(3)))
; __device__ __forceinline__ float rsq_f(float x) { return __builtin_amdgcn_rsqf(x); }
; __device__ __forceinline__ u32x4 pack8(const float* v) { u32x4 o; o.x = pk2(v[0], v[1]); o.y = pk2(v[2], v[3]); o.z = pk2(v[4], v[5]); o.w = pk2(v[6], v[7]); return o; }
; __device__ __forceinline__ void prep_task(LAS unsigned char* lds, const PrepP& P, int task, int tid, int lane, int wave) {
;     ...
;         { float sk = 0.f;
; #pragma unroll
;           for (int i = 0; i < 16; ++i) sk += x[i] * x[i];
;           sk += __shfl_xor(sk, 1); sk += __shfl_xor(sk, 2); sk += __shfl_xor(sk, 4);
;           const float rk = rsq_f(sk + EPS);
; #pragma unroll
;           for (int i = 0; i < 16; ++i) x[i] *= rk; }
;         *(LAS u32x4*)(Kl + lo) = pack8(x); *(LAS u32x4*)(Kl + lo + 8) = pack8(x + 8);
; #pragma unroll
;         for (int i = 0; i < 16; ++i) y[i] = x[i] * (beta * eg);
;         *(LAS u32x4*)(KBl + lo) = pack8(y); *(LAS u32x4*)(KBl + lo + 8) = pack8(y + 8);
; #pragma unroll
;         for (int i = 0; i < 16; ++i) y[i] = x[i] * et;
;         *(LAS u32x4*)(KTl + lo) = pack8(y); *(LAS u32x4*)(KTl + lo + 8) = pack8(y + 8);
;         asm volatile("" ::: "memory");
;         { float o[8]; conv8(xz[0][0], cw, o);
	v_pk_fma_f32 v[16:17], v[102:103], v[66:67], v[16:17]
	v_fmac_f32_e32 v78, v1, v1
	v_mul_f32_e32 v66, 0xbfb8aa3b, v16
	v_mul_f32_e32 v67, 0xbfb8aa3b, v17
	v_fmac_f32_e32 v78, v113, v113
	v_exp_f32_e32 v66, v66
	v_exp_f32_e32 v67, v67
	v_fmac_f32_e32 v78, v76, v76
	v_pk_mul_f32 v[20:21], v[20:21], v[22:23]
	v_fmac_f32_e32 v78, v77, v77
	v_pk_mul_f32 v[22:23], v[20:21], v[20:21]
	v_cndmask_b32_e64 v95, 0, v13, s[8:9]
	v_add_f32_e32 v23, v23, v78
	v_add_f32_e32 v68, v22, v23
	v_add_f32_e32 v22, 1.0, v66
	v_add_f32_e32 v23, 1.0, v67
	v_and_b32_e32 v67, 0xffff0000, v65
	v_lshlrev_b32_e32 v66, 16, v65
	v_pk_fma_f32 v[18:19], v[18:19], v[66:67], 0 op_sel_hi:[1,1,0]
	v_and_b32_e32 v65, 0xffff0000, v64
	v_lshlrev_b32_e32 v64, 16, v64
	v_pk_fma_f32 v[18:19], v[84:85], v[64:65], v[18:19]
	v_and_b32_e32 v65, 0xffff0000, v3
	v_lshlrev_b32_e32 v64, 16, v3
	v_pk_fma_f32 v[18:19], v[96:97], v[64:65], v[18:19]
	v_and_b32_e32 v3, 0xffff0000, v2
	v_lshlrev_b32_e32 v2, 16, v2
	v_pk_fma_f32 v[2:3], v[104:105], v[2:3], v[18:19]
	v_rcp_f32_e32 v22, v22
	v_mul_f32_e32 v18, 0xbfb8aa3b, v2
	v_exp_f32_e32 v64, v18
	v_mul_f32_e32 v18, 0xbfb8aa3b, v3
	v_rcp_f32_e32 v23, v23
	v_exp_f32_e32 v65, v18
	v_xor_b32_e32 v13, 2, v192
	v_cndmask_b32_e32 v94, 0, v0, vcc
	v_pk_mul_f32 v[18:19], v[16:17], v[22:23]
	v_add_f32_e32 v16, 1.0, v64
	v_add_f32_e32 v17, 1.0, v65
	v_rcp_f32_e32 v16, v16
	v_rcp_f32_e32 v17, v17
	v_pk_mul_f32 v[22:23], v[18:19], v[18:19]
	v_cndmask_b32_e64 v98, 0, v9, s[6:7]
	v_add_f32_e32 v22, v22, v68
	v_pk_mul_f32 v[2:3], v[2:3], v[16:17]
	v_add_f32_e32 v22, v23, v22
	v_pk_mul_f32 v[16:17], v[2:3], v[2:3]
	v_xor_b32_e32 v9, 4, v192
	v_add_f32_e32 v16, v16, v22
	v_and_b32_e32 v22, 64, v192
	v_add_f32_e32 v17, v17, v16
	v_xor_b32_e32 v16, 1, v192
	v_add_u32_e32 v22, 64, v22
	v_cmp_lt_i32_e64 s[14:15], v16, v22
	v_cmp_lt_i32_e32 vcc, v13, v22
	v_cndmask_b32_e64 v97, 0, v10, s[6:7]
	v_cndmask_b32_e64 v16, v192, v16, s[14:15]
	v_lshlrev_b32_e32 v16, 2, v16
	ds_bpermute_b32 v23, v16, v17
	v_cndmask_b32_e32 v13, v192, v13, vcc
	v_lshlrev_b32_e32 v13, 2, v13
	v_cmp_lt_i32_e32 vcc, v9, v22
	v_exp_f32_e32 v22, v62
	s_waitcnt lgkmcnt(0)
	v_add_f32_e32 v0, v17, v23
	ds_bpermute_b32 v17, v13, v0
	v_cndmask_b32_e32 v9, v192, v9, vcc
	v_lshlrev_b32_e32 v10, 2, v9
	v_cndmask_b32_e64 v96, 0, v12, s[8:9]
	v_cndmask_b32_e64 v12, 0, v7, s[10:11]
	s_waitcnt lgkmcnt(0)
	v_add_f32_e32 v0, v0, v17
	ds_bpermute_b32 v9, v10, v0
	v_cndmask_b32_e64 v17, 0, v8, s[6:7]
	v_exp_f32_e32 v8, v61
	v_cndmask_b32_e64 v99, 0, v6, s[10:11]
	v_cndmask_b32_e64 v100, 0, v5, s[10:11]
	s_waitcnt lgkmcnt(0)
	v_add_f32_e32 v0, v0, v9
	v_add_f32_e32 v0, 0x358637bd, v0
	v_rsq_f32_e32 v9, v0
	v_mov_b32_e32 v0, v25
	v_cndmask_b32_e64 v101, 0, v4, s[10:11]
	v_cndmask_b32_e64 v14, 0, v14, s[8:9]
	v_mul_f32_e32 v23, v88, v9
	v_mul_f32_e32 v61, v108, v9
	v_mul_f32_e32 v62, v109, v9
	v_mul_f32_e32 v64, v110, v9
	v_mul_f32_e32 v70, v2, v9
	v_mul_f32_e32 v71, v3, v9
	v_cvt_pk_bf16_f32 v2, v23, v61
	v_cvt_pk_bf16_f32 v3, v62, v64
	v_mul_f32_e32 v65, v111, v9
	v_mul_f32_e32 v66, v112, v9
	v_mul_f32_e32 v67, v113, v9
	v_mul_f32_e32 v68, v76, v9
	v_mul_f32_e32 v69, v77, v9
	v_mul_f32_e32 v21, v21, v9
	v_mul_f32_e32 v20, v20, v9
	v_mul_f32_e32 v18, v18, v9
	v_mul_f32_e32 v19, v19, v9
	v_cvt_pk_bf16_f32 v4, v65, v66
	v_pk_mul_f32 v[6:7], v[0:1], v[8:9]
	v_cvt_pk_bf16_f32 v0, v68, v69
	v_cvt_pk_bf16_f32 v1, v21, v20
	v_cndmask_b32_e64 v15, 0, v15, s[8:9]
	v_cvt_pk_bf16_f32 v5, v7, v67
	ds_write_b128 v60, v[2:5]
	v_cvt_pk_bf16_f32 v2, v18, v19
	v_cvt_pk_bf16_f32 v3, v70, v71
	ds_write_b128 v60, v[0:3] offset:16
	v_mul_f32_e32 v0, v6, v23
	v_mul_f32_e32 v1, v6, v61
	v_mul_f32_e32 v2, v6, v62
	v_mul_f32_e32 v3, v6, v64
	v_mul_f32_e32 v4, v6, v65
	v_mul_f32_e32 v5, v6, v66
	v_mul_f32_e32 v9, v6, v7
	v_mul_f32_e32 v25, v6, v67
	v_cvt_pk_bf16_f32 v0, v0, v1
	v_cvt_pk_bf16_f32 v1, v2, v3
	v_cvt_pk_bf16_f32 v2, v4, v5
	v_cvt_pk_bf16_f32 v3, v9, v25
	v_mul_f32_e32 v72, v6, v68
	v_mul_f32_e32 v73, v6, v69
	v_mul_f32_e32 v74, v6, v21
	v_mul_f32_e32 v75, v6, v20
	v_mul_f32_e32 v76, v6, v18
	v_mul_f32_e32 v77, v6, v19
	v_mul_f32_e32 v78, v6, v70
	v_mul_f32_e32 v6, v6, v71
	ds_write_b128 v60, v[0:3] offset:52224
	v_cvt_pk_bf16_f32 v0, v72, v73
	v_cvt_pk_bf16_f32 v1, v74, v75
	v_cvt_pk_bf16_f32 v2, v76, v77
	v_cvt_pk_bf16_f32 v3, v78, v6
	ds_write_b128 v60, v[0:3] offset:52240
	v_mul_f32_e32 v0, v22, v23
	v_mul_f32_e32 v1, v22, v61
	v_mul_f32_e32 v2, v22, v62
	v_mul_f32_e32 v3, v22, v64
	v_mul_f32_e32 v4, v22, v65
	v_mul_f32_e32 v5, v22, v66
	v_mul_f32_e32 v6, v22, v7
	v_mul_f32_e32 v7, v22, v67
	v_cvt_pk_bf16_f32 v0, v0, v1
	v_cvt_pk_bf16_f32 v1, v2, v3
	v_cvt_pk_bf16_f32 v2, v4, v5
	v_cvt_pk_bf16_f32 v3, v6, v7
	v_add_u32_e32 v4, v57, v89
	v_mul_f32_e32 v9, v22, v68
	v_mul_f32_e32 v23, v22, v69
	v_mul_f32_e32 v21, v22, v21
	v_mul_f32_e32 v20, v22, v20
	v_mul_f32_e32 v18, v22, v18
	v_mul_f32_e32 v19, v22, v19
	v_mul_f32_e32 v25, v22, v70
	v_mul_f32_e32 v22, v22, v71
	ds_write_b128 v4, v[0:3]
	v_cvt_pk_bf16_f32 v0, v9, v23
	v_cvt_pk_bf16_f32 v1, v21, v20
	v_cvt_pk_bf16_f32 v2, v18, v19
	v_cvt_pk_bf16_f32 v3, v25, v22
	ds_write_b128 v4, v[0:3] offset:16
	ds_read_b128 v[18:21], v31
	ds_read_b128 v[64:67], v31 offset:16
	ds_read_b128 v[4:7], v31 offset:32
	ds_read_b128 v[0:3], v31 offset:48
	ds_read_b128 v[68:71], v31 offset:1536
	ds_read_b128 v[72:75], v31 offset:1552
	ds_read_b128 v[76:79], v31 offset:3072
	ds_read_b128 v[80:83], v31 offset:3088
	ds_read_b128 v[84:87], v31 offset:4608
	ds_read_b128 v[88:91], v31 offset:4624
	v_lshlrev_b32_e32 v23, 16, v59
	v_lshlrev_b32_e32 v22, 16, v53
	s_waitcnt lgkmcnt(9)
; #define LAS __attribute__((address_space(3)))
; __device__ __forceinline__ float bflo(unsigned w) { return __uint_as_float(w << 16); }
; __device__ __forceinline__ float bfhi(unsigned w) { return __uint_as_float(w & 0xffff0000u); }
; __device__ __forceinline__ float silu_f(float x) { return x * rcp_f(1.f + exp_f(-x)); }
; __device__ __forceinline__ void conv8(const u32x4 (&x)[4], const LAS float* w, float (&o)[8]) {
;     f32x4 wa[4], wb[4];
; #pragma unroll
;     for (int j = 0; j < 4; ++j) { wa[j] = *(const LAS f32x4*)(w + j * 384); wb[j] = *(const LAS f32x4*)(w + j * 384 + 4); }
; #pragma unroll
;     for (int i = 0; i < 8; ++i) o[i] = 0.f;
; #pragma unroll
;     for (int j = 0; j < 4; ++j) {
;         o[0] += wa[j].x * bflo(x[j].x); o[1] += wa[j].y * bfhi(x[j].x); o[2] += wa[j].z * bflo(x[j].y); o[3] += wa[j].w * bfhi(x[j].y);
;         o[4] += wb[j].x * bflo(x[j].z); o[5] += wb[j].y * bfhi(x[j].z); o[6] += wb[j].z * bflo(x[j].w); o[7] += wb[j].w * bfhi(x[j].w); }
; #pragma unroll
;     for (int i = 0; i < 8; ++i) o[i] = silu_f(o[i]);
; __device__ __forceinline__ void prep_task(LAS unsigned char* lds, const PrepP& P, int task, int tid, int lane, int wave) {
;     ...
;         { float o[8]; conv8(xz[0][0], cw, o);
; #pragma unroll
;           for (int i = 0; i < 8; ++i) x[i] = o[i];
;           conv8(xz[0][1], cw + 8, o);
; #pragma unroll
;           for (int i = 0; i < 8; ++i) x[8 + i] = o[i]; }
	v_mov_b32_e32 v92, v18
	s_waitcnt lgkmcnt(5)
	v_mov_b32_e32 v93, v68
	v_pk_mul_f32 v[22:23], v[92:93], v[22:23]
	v_mov_b32_e32 v68, v19
	v_add_f32_e32 v9, 0, v22
	v_add_f32_e32 v9, v9, v23
	v_and_b32_e32 v23, 0xffff0000, v59
	v_and_b32_e32 v22, 0xffff0000, v53
	v_pk_mul_f32 v[18:19], v[68:69], v[22:23]
	v_mov_b32_e32 v22, v20
	v_add_f32_e32 v18, 0, v18
	v_add_f32_e32 v25, v18, v19
	v_lshlrev_b32_e32 v19, 16, v52
	v_lshlrev_b32_e32 v18, 16, v51
	v_mov_b32_e32 v23, v70
	v_pk_mul_f32 v[18:19], v[22:23], v[18:19]
	v_mov_b32_e32 v70, v21
	v_add_f32_e32 v18, 0, v18
	v_add_f32_e32 v22, v18, v19
	v_and_b32_e32 v19, 0xffff0000, v52
	v_and_b32_e32 v18, 0xffff0000, v51
	v_pk_mul_f32 v[18:19], v[70:71], v[18:19]
	v_mov_b32_e32 v20, v64
	v_add_f32_e32 v18, 0, v18
	v_add_f32_e32 v23, v18, v19
	v_lshlrev_b32_e32 v19, 16, v50
	v_lshlrev_b32_e32 v18, 16, v49
	s_waitcnt lgkmcnt(4)
	v_mov_b32_e32 v21, v72
	v_pk_mul_f32 v[18:19], v[20:21], v[18:19]
	v_mov_b32_e32 v72, v65
	v_add_f32_e32 v18, 0, v18
	v_add_f32_e32 v51, v18, v19
	v_and_b32_e32 v19, 0xffff0000, v50
	v_and_b32_e32 v18, 0xffff0000, v49
	v_pk_mul_f32 v[18:19], v[72:73], v[18:19]
	v_mov_b32_e32 v20, v66
	v_add_f32_e32 v18, 0, v18
	v_add_f32_e32 v49, v18, v19
	v_lshlrev_b32_e32 v19, 16, v39
	v_lshlrev_b32_e32 v18, 16, v38
	v_mov_b32_e32 v21, v74
	v_pk_mul_f32 v[18:19], v[20:21], v[18:19]
	v_mov_b32_e32 v74, v67
	v_add_f32_e32 v18, 0, v18
	v_add_f32_e32 v50, v18, v19
	v_and_b32_e32 v19, 0xffff0000, v39
	v_and_b32_e32 v18, 0xffff0000, v38
	v_pk_mul_f32 v[18:19], v[74:75], v[18:19]
	s_waitcnt lgkmcnt(3)
	v_mov_b32_e32 v20, v76
	v_add_f32_e32 v18, 0, v18
	v_add_f32_e32 v38, v18, v19
	v_lshlrev_b32_e32 v18, 16, v37
	v_lshlrev_b32_e32 v19, 16, v36
	s_waitcnt lgkmcnt(1)
	v_mov_b32_e32 v21, v84
	v_pk_mul_f32 v[18:19], v[20:21], v[18:19]
	v_mov_b32_e32 v84, v77
	v_add_f32_e32 v9, v9, v18
	v_add_f32_e32 v9, v9, v19
	v_and_b32_e32 v19, 0xffff0000, v36
	v_and_b32_e32 v18, 0xffff0000, v37
	v_pk_mul_f32 v[18:19], v[84:85], v[18:19]
	v_mov_b32_e32 v20, v78
	v_add_f32_e32 v18, v25, v18
	v_add_f32_e32 v25, v18, v19
	v_lshlrev_b32_e32 v18, 16, v35
	v_lshlrev_b32_e32 v19, 16, v34
	v_mov_b32_e32 v21, v86
	v_pk_mul_f32 v[18:19], v[20:21], v[18:19]
	v_mov_b32_e32 v86, v79
	v_add_f32_e32 v18, v22, v18
	v_add_f32_e32 v22, v18, v19
	v_and_b32_e32 v19, 0xffff0000, v34
	v_and_b32_e32 v18, 0xffff0000, v35
	v_pk_mul_f32 v[18:19], v[86:87], v[18:19]
	v_mov_b32_e32 v20, v80
	v_add_f32_e32 v18, v23, v18
	v_add_f32_e32 v23, v18, v19
	v_lshlrev_b32_e32 v18, 16, v33
	v_lshlrev_b32_e32 v19, 16, v32
	s_waitcnt lgkmcnt(0)
	v_mov_b32_e32 v21, v88
	v_pk_mul_f32 v[18:19], v[20:21], v[18:19]
	v_mov_b32_e32 v88, v81
	v_add_f32_e32 v18, v51, v18
	v_add_f32_e32 v34, v18, v19
	v_and_b32_e32 v19, 0xffff0000, v32
	v_and_b32_e32 v18, 0xffff0000, v33
	v_pk_mul_f32 v[18:19], v[88:89], v[18:19]
	v_mov_b32_e32 v20, v82
	v_add_f32_e32 v18, v49, v18
	v_add_f32_e32 v32, v18, v19
	v_lshlrev_b32_e32 v18, 16, v30
	v_lshlrev_b32_e32 v19, 16, v29
	v_mov_b32_e32 v21, v90
	v_pk_mul_f32 v[18:19], v[20:21], v[18:19]
	v_mul_f32_e32 v21, 0xbfb8aa3b, v9
	v_add_f32_e32 v18, v50, v18
	v_exp_f32_e32 v21, v21
	v_add_f32_e32 v20, v18, v19
	v_and_b32_e32 v19, 0xffff0000, v29
	v_and_b32_e32 v18, 0xffff0000, v30
	v_mov_b32_e32 v90, v83
	v_pk_mul_f32 v[18:19], v[90:91], v[18:19]
	v_mul_f32_e32 v29, 0xbfb8aa3b, v22
	v_add_f32_e32 v18, v38, v18
	v_add_f32_e32 v18, v18, v19
	v_add_f32_e32 v19, 1.0, v21
	v_mul_f32_e32 v21, 0xbfb8aa3b, v25
	v_exp_f32_e32 v21, v21
	v_exp_f32_e32 v29, v29
	v_mul_f32_e32 v30, 0xbfb8aa3b, v23
	v_rcp_f32_e32 v19, v19
	v_add_f32_e32 v21, 1.0, v21
	v_add_f32_e32 v29, 1.0, v29
	v_rcp_f32_e32 v21, v21
	v_rcp_f32_e32 v29, v29
	v_exp_f32_e32 v30, v30
	v_mul_f32_e32 v9, v9, v19
	v_mul_f32_e32 v25, v25, v21
	v_mul_f32_e32 v29, v22, v29
	v_add_f32_e32 v19, 1.0, v30
	v_mul_f32_e32 v21, 0xbfb8aa3b, v34
	v_mul_f32_e32 v22, 0xbfb8aa3b, v32
	v_rcp_f32_e32 v19, v19
	v_exp_f32_e32 v21, v21
	v_exp_f32_e32 v22, v22
	v_mov_b32_e32 v30, v4
	v_mul_f32_e32 v49, v23, v19
	v_add_f32_e32 v19, 1.0, v21
	v_add_f32_e32 v21, 1.0, v22
	v_mul_f32_e32 v22, 0xbfb8aa3b, v20
	v_mul_f32_e32 v23, 0xbfb8aa3b, v18
	v_exp_f32_e32 v22, v22
	v_exp_f32_e32 v23, v23
	v_rcp_f32_e32 v19, v19
	v_rcp_f32_e32 v21, v21
	v_add_f32_e32 v22, 1.0, v22
	v_add_f32_e32 v23, 1.0, v23
	v_rcp_f32_e32 v22, v22
	v_rcp_f32_e32 v23, v23
	v_mul_f32_e32 v61, v34, v19
	v_mul_f32_e32 v72, v32, v21
	v_mul_f32_e32 v73, v20, v22
	v_mul_f32_e32 v74, v18, v23
	ds_read_b128 v[18:21], v31 offset:1568
	ds_read_b128 v[32:35], v31 offset:1584
	ds_read_b128 v[36:39], v31 offset:3104
	ds_read_b128 v[50:53], v31 offset:3120
	ds_read_b128 v[64:67], v31 offset:4640
	ds_read_b128 v[68:71], v31 offset:4656
	v_lshlrev_b32_e32 v23, 16, v96
	v_lshlrev_b32_e32 v22, 16, v94
	s_waitcnt lgkmcnt(5)
	v_mov_b32_e32 v31, v18
	v_pk_mul_f32 v[22:23], v[30:31], v[22:23]
	v_mov_b32_e32 v18, v5
	v_add_f32_e32 v4, 0, v22
	v_add_f32_e32 v30, v4, v23
	v_and_b32_e32 v23, 0xffff0000, v96
	v_and_b32_e32 v22, 0xffff0000, v94
	v_pk_mul_f32 v[4:5], v[18:19], v[22:23]
	v_mov_b32_e32 v18, v6
	v_add_f32_e32 v4, 0, v4
	v_add_f32_e32 v22, v4, v5
	v_lshlrev_b32_e32 v5, 16, v95
	v_lshlrev_b32_e32 v4, 16, v28
	v_mov_b32_e32 v19, v20
	v_pk_mul_f32 v[4:5], v[18:19], v[4:5]
	v_mov_b32_e32 v20, v7
	v_add_f32_e32 v4, 0, v4
	v_add_f32_e32 v18, v4, v5
	v_and_b32_e32 v5, 0xffff0000, v95
	v_and_b32_e32 v4, 0xffff0000, v28
	v_pk_mul_f32 v[4:5], v[20:21], v[4:5]
	s_waitcnt lgkmcnt(3)
	v_mov_b32_e32 v6, v36
	v_add_f32_e32 v4, 0, v4
	v_add_f32_e32 v19, v4, v5
	v_lshlrev_b32_e32 v5, 16, v101
	v_lshlrev_b32_e32 v4, 16, v17
	s_waitcnt lgkmcnt(1)
; #define LAS __attribute__((address_space(3)))
; __device__ __forceinline__ float rsq_f(float x) { return __builtin_amdgcn_rsqf(x); }
; #define LBAR() do { asm volatile("s_waitcnt lgkmcnt(0)" ::: "memory"); __builtin_amdgcn_s_barrier(); asm volatile("" ::: "memory"); } while (0)
; __device__ __forceinline__ u32x4 pack8(const float* v) { u32x4 o; o.x = pk2(v[0], v[1]); o.y = pk2(v[2], v[3]); o.z = pk2(v[4], v[5]); o.w = pk2(v[6], v[7]); return o; }
; __device__ __forceinline__ void prep_task(LAS unsigned char* lds, const PrepP& P, int task, int tid, int lane, int wave) {
;     ...
;         { float o[8]; conv8(xz[0][0], cw, o);
; #pragma unroll
;           for (int i = 0; i < 8; ++i) x[i] = o[i];
;           conv8(xz[0][1], cw + 8, o);
; #pragma unroll
;           for (int i = 0; i < 8; ++i) x[8 + i] = o[i]; }
;         { float sq = 0.f;
; #pragma unroll
;           for (int i = 0; i < 16; ++i) sq += x[i] * x[i];
;           sq += __shfl_xor(sq, 1); sq += __shfl_xor(sq, 2); sq += __shfl_xor(sq, 4);
;           const float rq = rsq_f(sq + EPS) * 0.08838834764831845f;
; #pragma unroll
;           for (int i = 0; i < 16; ++i) x[i] *= rq; }
;         *(LAS u32x4*)(Ql + lo) = pack8(x); *(LAS u32x4*)(Ql + lo + 8) = pack8(x + 8);
; #pragma unroll
;         for (int i = 0; i < 16; ++i) y[i] = x[i] * eg;
;         bf16_t* qo = (bf16_t*)(trp + TR_Q) + t * 128 + seg * 16;
;         *(u32x4*)qo = pack8(y); *(u32x4*)(qo + 8) = pack8(y + 8);
;     }
;     LBAR();
;     {
;         const int it = wave >> 1, jt0 = (wave & 1) * 2;
;         bf16x8 aK[4], aQ[4];
; #pragma unroll
;         for (int ks = 0; ks < 4; ++ks) { aK[ks] = *(const LAS bf16x8*)(Kl + (it * 16 + r) * PS + ks * 32 + q8 * 8); aQ[ks] = *(const LAS bf16x8*)(Ql + (it * 16 + r) * PS + ks * 32 + q8 * 8); }
	v_mov_b32_e32 v7, v64
	v_pk_mul_f32 v[4:5], v[6:7], v[4:5]
	v_mov_b32_e32 v64, v37
	v_add_f32_e32 v4, v30, v4
	v_add_f32_e32 v20, v4, v5
	v_and_b32_e32 v5, 0xffff0000, v101
	v_and_b32_e32 v4, 0xffff0000, v17
	v_pk_mul_f32 v[4:5], v[64:65], v[4:5]
	v_mov_b32_e32 v6, v38
	v_add_f32_e32 v4, v22, v4
	v_add_f32_e32 v17, v4, v5
	v_lshlrev_b32_e32 v5, 16, v100
	v_lshlrev_b32_e32 v4, 16, v98
	v_mov_b32_e32 v7, v66
	v_pk_mul_f32 v[4:5], v[6:7], v[4:5]
	v_mov_b32_e32 v66, v39
	v_add_f32_e32 v4, v18, v4
	v_add_f32_e32 v6, v4, v5
	v_and_b32_e32 v5, 0xffff0000, v100
	v_and_b32_e32 v4, 0xffff0000, v98
	v_pk_mul_f32 v[4:5], v[66:67], v[4:5]
	v_mul_f32_e32 v7, 0xbfb8aa3b, v20
	v_add_f32_e32 v4, v19, v4
	v_add_f32_e32 v4, v4, v5
	v_mul_f32_e32 v18, 0xbfb8aa3b, v17
	v_mul_f32_e32 v19, 0xbfb8aa3b, v4
	v_exp_f32_e32 v7, v7
	v_exp_f32_e32 v18, v18
	v_exp_f32_e32 v19, v19
	v_cndmask_b32_e64 v11, 0, v11, s[6:7]
	v_add_f32_e32 v5, 1.0, v7
	v_add_f32_e32 v7, 1.0, v18
	v_mul_f32_e32 v18, 0xbfb8aa3b, v6
	v_add_f32_e32 v19, 1.0, v19
	v_rcp_f32_e32 v5, v5
	v_exp_f32_e32 v18, v18
	v_rcp_f32_e32 v19, v19
	v_rcp_f32_e32 v7, v7
	v_mul_f32_e32 v20, v20, v5
	v_add_f32_e32 v18, 1.0, v18
	v_mul_f32_e32 v19, v4, v19
	v_and_b32_e32 v5, 0xffff0000, v27
	v_lshlrev_b32_e32 v4, 16, v27
	v_rcp_f32_e32 v18, v18
	v_pk_fma_f32 v[0:1], v[0:1], v[4:5], 0 op_sel_hi:[1,1,0]
	v_and_b32_e32 v5, 0xffff0000, v14
	v_lshlrev_b32_e32 v4, 16, v14
	v_pk_fma_f32 v[0:1], v[32:33], v[4:5], v[0:1]
	v_and_b32_e32 v5, 0xffff0000, v97
	v_lshlrev_b32_e32 v4, 16, v97
	v_pk_fma_f32 v[0:1], v[50:51], v[4:5], v[0:1]
	v_and_b32_e32 v5, 0xffff0000, v99
	v_lshlrev_b32_e32 v4, 16, v99
	s_waitcnt lgkmcnt(0)
	v_pk_fma_f32 v[0:1], v[68:69], v[4:5], v[0:1]
	v_mul_f32_e32 v17, v17, v7
	v_mul_f32_e32 v18, v6, v18
	v_mul_f32_e32 v4, 0xbfb8aa3b, v0
	v_mul_f32_e32 v5, 0xbfb8aa3b, v1
	v_and_b32_e32 v7, 0xffff0000, v24
	v_lshlrev_b32_e32 v6, 16, v24
	v_exp_f32_e32 v4, v4
	v_exp_f32_e32 v5, v5
	v_pk_fma_f32 v[2:3], v[2:3], v[6:7], 0 op_sel_hi:[1,1,0]
	v_and_b32_e32 v7, 0xffff0000, v15
	v_lshlrev_b32_e32 v6, 16, v15
	v_pk_fma_f32 v[2:3], v[34:35], v[6:7], v[2:3]
	v_and_b32_e32 v7, 0xffff0000, v11
	v_lshlrev_b32_e32 v6, 16, v11
	v_mul_f32_e32 v21, v25, v25
	v_pk_fma_f32 v[2:3], v[52:53], v[6:7], v[2:3]
	v_and_b32_e32 v7, 0xffff0000, v12
	v_lshlrev_b32_e32 v6, 16, v12
	v_fmac_f32_e32 v21, v9, v9
	v_pk_fma_f32 v[2:3], v[70:71], v[6:7], v[2:3]
	v_fmac_f32_e32 v21, v29, v29
	v_add_f32_e32 v4, 1.0, v4
	v_add_f32_e32 v5, 1.0, v5
	v_mul_f32_e32 v6, 0xbfb8aa3b, v2
	v_mul_f32_e32 v7, 0xbfb8aa3b, v3
	v_fmac_f32_e32 v21, v49, v49
	v_rcp_f32_e32 v4, v4
	v_rcp_f32_e32 v5, v5
	v_exp_f32_e32 v6, v6
	v_exp_f32_e32 v7, v7
	v_fmac_f32_e32 v21, v61, v61
	v_fmac_f32_e32 v21, v72, v72
	v_fmac_f32_e32 v21, v73, v73
	v_fmac_f32_e32 v21, v74, v74
	v_pk_mul_f32 v[0:1], v[0:1], v[4:5]
	v_add_f32_e32 v4, 1.0, v6
	v_add_f32_e32 v5, 1.0, v7
	v_fmac_f32_e32 v21, v20, v20
	v_rcp_f32_e32 v4, v4
	v_rcp_f32_e32 v5, v5
	v_fmac_f32_e32 v21, v17, v17
	v_fmac_f32_e32 v21, v18, v18
	v_fmac_f32_e32 v21, v19, v19
	v_pk_mul_f32 v[6:7], v[0:1], v[0:1]
	v_pk_mul_f32 v[2:3], v[2:3], v[4:5]
	v_add_f32_e32 v6, v6, v21
	v_add_f32_e32 v6, v7, v6
	v_pk_mul_f32 v[4:5], v[2:3], v[2:3]
	s_mov_b32 s6, 0x22404000
	v_add_f32_e32 v4, v4, v6
	v_add_f32_e32 v4, v5, v4
	ds_bpermute_b32 v5, v16, v4
	v_and_b32_e32 v59, 15, v55
	v_or_b32_e32 v65, s34, v59
	v_lshlrev_b32_e32 v32, 6, v65
	v_ashrrev_i32_e32 v33, 31, v32
	s_waitcnt lgkmcnt(0)
	v_add_f32_e32 v4, v4, v5
	ds_bpermute_b32 v5, v13, v4
	v_lshrrev_b32_e32 v62, 4, v56
	v_lshlrev_b64 v[32:33], 1, v[32:33]
	v_lshlrev_b32_e32 v75, 2, v62
	v_add_u32_e32 v64, 0x15400, v58
	s_waitcnt lgkmcnt(0)
	v_add_f32_e32 v4, v4, v5
	ds_bpermute_b32 v5, v10, v4
	v_lshl_add_u32 v66, v65, 2, v63
	s_waitcnt lgkmcnt(0)
	v_add_f32_e32 v4, v4, v5
	v_add_f32_e32 v4, 0x358637bd, v4
	v_rsq_f32_e32 v4, v4
	s_nop 0
	v_mul_f32_e32 v4, 0x3db504f3, v4
	v_mul_f32_e32 v5, v9, v4
	v_mul_f32_e32 v6, v25, v4
	v_mul_f32_e32 v16, v18, v4
	v_mul_f32_e32 v18, v0, v4
	v_cvt_pk_bf16_f32 v0, v5, v6
	v_mul_f32_e32 v7, v29, v4
	v_mul_f32_e32 v9, v49, v4
	v_mul_f32_e32 v10, v61, v4
	v_mul_f32_e32 v11, v72, v4
	v_mul_f32_e32 v12, v73, v4
	v_mul_f32_e32 v13, v74, v4
	v_mul_f32_e32 v14, v20, v4
	v_mul_f32_e32 v15, v17, v4
	v_mul_f32_e32 v17, v19, v4
	v_mul_f32_e32 v19, v1, v4
	v_mul_f32_e32 v20, v2, v4
	v_mul_f32_e32 v4, v3, v4
	v_cvt_pk_bf16_f32 v1, v7, v9
	v_cvt_pk_bf16_f32 v2, v10, v11
	v_cvt_pk_bf16_f32 v3, v12, v13
	ds_write_b128 v60, v[0:3] offset:17408
	v_cvt_pk_bf16_f32 v0, v14, v15
	v_cvt_pk_bf16_f32 v1, v16, v17
	v_cvt_pk_bf16_f32 v2, v18, v19
	v_cvt_pk_bf16_f32 v3, v20, v4
	ds_write_b128 v60, v[0:3] offset:17424
	v_lshlrev_b32_e32 v0, 7, v26
	v_ashrrev_i32_e32 v1, 31, v0
	v_mul_f32_e32 v2, v8, v5
	v_mul_f32_e32 v3, v8, v6
	v_mul_f32_e32 v6, v8, v7
	v_mul_f32_e32 v7, v8, v9
	v_mul_f32_e32 v9, v8, v10
	v_mul_f32_e32 v10, v8, v11
	v_mul_f32_e32 v11, v8, v12
	v_mul_f32_e32 v12, v8, v13
	v_mul_f32_e32 v13, v8, v14
	v_mul_f32_e32 v14, v8, v15
	v_mul_f32_e32 v15, v8, v16
	v_mul_f32_e32 v16, v8, v17
	v_mul_f32_e32 v17, v8, v18
	v_mul_f32_e32 v18, v8, v19
	v_mul_f32_e32 v19, v8, v20
	v_mul_f32_e32 v8, v8, v4
	v_and_b32_e32 v4, 7, v55
	v_lshlrev_b64 v[0:1], 1, v[0:1]
	v_lshl_or_b32 v0, v4, 5, v0
	v_lshl_add_u64 v[0:1], s[26:27], 0, v[0:1]
	v_lshl_add_u64 v[4:5], v[40:41], 0, v[0:1]
	v_add_co_u32_e32 v4, vcc, s6, v4
	v_cvt_pk_bf16_f32 v0, v2, v3
	v_cvt_pk_bf16_f32 v1, v6, v7
	v_cvt_pk_bf16_f32 v2, v9, v10
	v_cvt_pk_bf16_f32 v3, v11, v12
	s_nop 1
	v_addc_co_u32_e32 v5, vcc, 0, v5, vcc
	global_store_dwordx4 v[4:5], v[0:3], off
	v_and_b32_e32 v61, 48, v55
	v_lshrrev_b32_e32 v60, 1, v61
	v_cvt_pk_bf16_f32 v0, v13, v14
	v_cvt_pk_bf16_f32 v1, v15, v16
	v_cvt_pk_bf16_f32 v2, v17, v18
	v_cvt_pk_bf16_f32 v3, v19, v8
	global_store_dwordx4 v[4:5], v[0:3], off offset:16
	s_waitcnt lgkmcnt(0)
	s_barrier
	v_or_b32_e32 v32, v32, v60
	v_mul_lo_u32 v0, v65, s51
	v_and_b32_e32 v1, 48, v56
	v_add3_u32 v12, v58, v0, v1
	ds_read_b128 v[24:27], v12
	ds_read_b128 v[4:7], v12 offset:64
	ds_read_b128 v[28:31], v12 offset:17408
	ds_read_b128 v[16:19], v12 offset:17472
	ds_read_b128 v[8:11], v12 offset:128
	ds_read_b128 v[0:3], v12 offset:192
	ds_read_b128 v[20:23], v12 offset:17536
	ds_read_b128 v[12:15], v12 offset:17600
	v_or_b32_e32 v72, s34, v75
	v_lshl_add_u64 v[32:33], s[28:29], 0, v[32:33]
	v_lshl_add_u64 v[50:51], v[40:41], 0, v[32:33]
	s_mov_b64 s[6:7], 0x22408000
	v_or_b32_e32 v71, 1, v72
	v_or_b32_e32 v69, 2, v72
	v_or_b32_e32 v67, 3, v72
	v_add_u32_e32 v76, v58, v61
	v_lshl_add_u64 v[52:53], v[50:51], 0, s[6:7]
	s_mov_b64 s[6:7], -1
	s_andn2_b64 vcc, exec, s[18:19]
	v_lshl_add_u32 v74, v72, 2, v63
	v_lshl_add_u32 v73, v71, 2, v63
	v_lshl_add_u32 v70, v69, 2, v63
	v_lshl_add_u32 v68, v67, 2, v63
	s_cbranch_vccz .LBB0_427
	v_lshl_add_u32 v33, v59, 2, v64
	s_andn2_b64 vcc, exec, s[6:7]
	v_lshlrev_b32_e32 v32, 8, v72
	s_cbranch_vccz .LBB0_428

; __global__ void __launch_bounds__(512, 2) mega(Args a) {
;     extern __shared__ __attribute__((aligned(16))) unsigned char lds_raw[];
	.amdhsa_kernel _Z4mega4Args
		.amdhsa_group_segment_fixed_size 0
		.amdhsa_private_segment_fixed_size 0
		.amdhsa_kernarg_size 416
		.amdhsa_user_sgpr_count 2
		.amdhsa_user_sgpr_dispatch_ptr 0
		.amdhsa_user_sgpr_queue_ptr 0
		.amdhsa_user_sgpr_kernarg_segment_ptr 1
		.amdhsa_user_sgpr_dispatch_id 0
		.amdhsa_user_sgpr_kernarg_preload_length 0
		.amdhsa_user_sgpr_kernarg_preload_offset 0
		.amdhsa_user_sgpr_private_segment_size 0
		.amdhsa_uses_dynamic_stack 0
		.amdhsa_enable_private_segment 0
		.amdhsa_system_sgpr_workgroup_id_x 1
		.amdhsa_system_sgpr_workgroup_id_y 0
		.amdhsa_system_sgpr_workgroup_id_z 0
		.amdhsa_system_sgpr_workgroup_info 0
		.amdhsa_system_vgpr_workitem_id 2
		.amdhsa_next_free_vgpr 255
		.amdhsa_next_free_sgpr 102
		.amdhsa_accum_offset 256
		.amdhsa_reserve_vcc 1
		.amdhsa_float_round_mode_32 0
		.amdhsa_float_round_mode_16_64 0
		.amdhsa_float_denorm_mode_32 3
		.amdhsa_float_denorm_mode_16_64 3
		.amdhsa_dx10_clamp 1
		.amdhsa_ieee_mode 1
		.amdhsa_fp16_overflow 0
		.amdhsa_tg_split 0
		.amdhsa_exception_fp_ieee_invalid_op 0
		.amdhsa_exception_fp_denorm_src 0
		.amdhsa_exception_fp_ieee_div_zero 0
		.amdhsa_exception_fp_ieee_overflow 0
		.amdhsa_exception_fp_ieee_underflow 0
		.amdhsa_exception_fp_ieee_inexact 0
		.amdhsa_exception_int_div_zero 0
	.end_amdhsa_kernel

; __global__ void __launch_bounds__(512, 2) mega(Args a) {
;     extern __shared__ __attribute__((aligned(16))) unsigned char lds_raw[];
amdhsa.kernels:
  - .agpr_count:     0
    .args:
      - .offset:         0
        .size:           160
        .value_kind:     by_value
      - .offset:         160
        .size:           4
        .value_kind:     hidden_block_count_x
      - .offset:         164
        .size:           4
        .value_kind:     hidden_block_count_y
      - .offset:         168
        .size:           4
        .value_kind:     hidden_block_count_z
      - .offset:         172
        .size:           2
        .value_kind:     hidden_group_size_x
      - .offset:         174
        .size:           2
        .value_kind:     hidden_group_size_y
      - .offset:         176
        .size:           2
        .value_kind:     hidden_group_size_z
      - .offset:         178
        .size:           2
        .value_kind:     hidden_remainder_x
      - .offset:         180
        .size:           2
        .value_kind:     hidden_remainder_y
      - .offset:         182
        .size:           2
        .value_kind:     hidden_remainder_z
      - .offset:         200
        .size:           8
        .value_kind:     hidden_global_offset_x
      - .offset:         208
        .size:           8
        .value_kind:     hidden_global_offset_y
      - .offset:         216
        .size:           8
        .value_kind:     hidden_global_offset_z
      - .offset:         224
        .size:           2
        .value_kind:     hidden_grid_dims
      - .offset:         248
        .size:           8
        .value_kind:     hidden_multigrid_sync_arg
      - .offset:         280
        .size:           4
        .value_kind:     hidden_dynamic_lds_size
    .group_segment_fixed_size: 0
    .kernarg_segment_align: 8
    .kernarg_segment_size: 416
    .language:       OpenCL C
    .language_version:
      - 2
      - 0
    .max_flat_workgroup_size: 512
    .name:           _Z4mega4Args
    .private_segment_fixed_size: 0
    .sgpr_count:     108
    .sgpr_spill_count: 10
    .symbol:         _Z4mega4Args.kd
    .uniform_work_group_size: 1
    .uses_dynamic_stack: false
    .vgpr_count:     255
    .vgpr_spill_count: 0
    .wavefront_size: 64
